# mixC: gate G loads at item top, NP/CT fragment loads issued behind the VTs loads (in flight across gate chain and barriers)
# baseline (speedup 1.0000x reference)
; DI unsigned pack2(float a, float b) { const f32x2 v = {a, b}; return __builtin_bit_cast(unsigned, __builtin_convertvector(v, bf16v2)); }
; DI void conv_unit(const u16* __restrict__ PM, const float* __restrict__ conv_w, const float* __restrict__ conv_b, int b, int sl0, int ch, float scale, float* a8) {
;   { const float4 b0 = *(const float4*)(conv_b + ch), b1 = *(const float4*)(conv_b + ch + 4); a8[0] = b0.x; a8[1] = b0.y; a8[2] = b0.z; a8[3] = b0.w; a8[4] = b1.x; a8[5] = b1.y; a8[6] = b1.z; a8[7] = b1.w; }
; #pragma unroll
;   for (int j = 0; j < 4; ++j) {
;     const int sl = sl0 - 3 + j;
;     if (sl >= 0) {
;       const uint4 raw = *(const uint4*)(PM + ((size_t)b * SEQ + sl) * 1024 + ch);
;       float x8[8]; unpack8(raw, x8);
;       const float4 w0 = *(const float4*)(conv_w + j * 1024 + ch), w1 = *(const float4*)(conv_w + j * 1024 + ch + 4);
;       a8[0] += w0.x * x8[0]; a8[1] += w0.y * x8[1]; a8[2] += w0.z * x8[2]; a8[3] += w0.w * x8[3];
;       a8[4] += w1.x * x8[4]; a8[5] += w1.y * x8[5]; a8[6] += w1.z * x8[6]; a8[7] += w1.w * x8[7];
;     }
;   }
; DI void mlstmC_pair(const Params& p, char* lds_all, int pair) {
;     ...
; #pragma unroll 1
;   for (int i = 0; i < 8; ++i) {
;     const int cg8 = ltid & 31, isK = cg8 >> 4, chl = (cg8 & 15) * 8, t = (ltid >> 5) + 8 * i;
;     float a8[8];
;     conv_unit(PM, p.in[5], p.in[6], b, c * 64 + t, (isK ? 512 : 0) + hd * 128 + chl, isK ? 0.08838834764831845f : 1.f, a8);
;     uint4 o; o.x = pack2(a8[0], a8[1]); o.y = pack2(a8[2], a8[3]); o.z = pack2(a8[4], a8[5]); o.w = pack2(a8[6], a8[7]);
;     *(uint4*)((isK ? Ks : Qs) + t * 136 + chl) = o;
;   }
;   for (int i = 0; i < 4; ++i) {
;     const int q = ltid + 256 * i, e = q >> 3, s8 = (q & 7) * 8;
;     *(uint4*)(VTs + e * 72 + s8) = *(const uint4*)(VTm + ((size_t)(bh * 128 + e)) * SEQ + c * 64 + s8);
;   }
;   if (lwave == 0) {
;     const size_t row = (size_t)b * SEQ + c * 64 + lane;
;     const float ig = G[row * 8 + hd] + p.in[7][hd], fg = G[row * 8 + 4 + hd] + p.in[8][hd];
.LBB0_572:
	s_or_b64 exec, exec, s[0:1]
	v_ashrrev_i32_e32 v16, 9, v45
	v_bfe_u32 v44, v45, 7, 2
	v_lshlrev_b32_e32 v52, 3, v46
	v_and_b32_e32 v26, 16, v46
	v_lshlrev_b32_e32 v47, 7, v44
	v_and_b32_e32 v33, 0x78, v52
	v_lshlrev_b32_e32 v36, 5, v26
	v_ashrrev_i32_e32 v17, 31, v16
	v_lshlrev_b64 v[200:201], 13, v[16:17]
	v_and_b32_e32 v202, 63, v46
	v_lshl_or_b32 v202, v53, 6, v202
	v_or_b32_e32 v200, v200, v202
	v_lshlrev_b64 v[200:201], 5, v[200:201]
	v_lshl_or_b32 v200, v44, 2, v200
	v_lshl_add_u64 v[200:201], s[52:53], 0, v[200:201]
	v_lshlrev_b32_e32 v202, 2, v44
	global_load_dword v182, v[200:201], off
	global_load_dword v220, v[200:201], off offset:16
	global_load_dword v221, v202, s[66:67]
	global_load_dword v223, v202, s[36:37]
	v_or3_b32 v2, v47, v36, v33
	v_lshlrev_b64 v[34:35], 24, v[16:17]
	v_lshl_add_u64 v[0:1], s[40:41], 0, v[34:35]
	v_lshlrev_b32_e32 v20, 1, v2
	v_lshl_add_u64 v[18:19], v[0:1], 0, v[20:21]
	v_lshlrev_b32_e32 v20, 2, v2
	v_lshl_add_u64 v[22:23], s[62:63], 0, v[20:21]
	s_mov_b64 s[0:1], 0x3000
	v_lshl_add_u64 v[12:13], v[22:23], 0, s[0:1]
	s_movk_i32 s0, 0x3000
	v_add_co_u32_e64 v8, s[0:1], s0, v22
	global_load_dwordx4 v[0:3], v20, s[64:65] offset:16
	global_load_dwordx4 v[4:7], v20, s[64:65]
	v_addc_co_u32_e64 v9, s[0:1], 0, v23, s[0:1]
	global_load_dwordx4 v[8:11], v[8:9], off
	s_nop 0
	global_load_dwordx4 v[12:15], v[12:13], off offset:16
	s_mov_b32 s0, 0x11000
	v_mad_i32_i24 v51, v32, s0, 0
	v_add_u32_e32 v20, 0x4400, v51
	v_bfe_u32 v38, v46, 5, 3
	v_cmp_eq_u32_e64 s[0:1], 0, v26
	v_and_b32_e32 v40, 15, v46
	v_add_u32_e32 v32, s16, v32
	v_lshrrev_b32_e32 v37, 8, v46
	v_cndmask_b32_e64 v20, v20, v51, s[0:1]
	v_mul_u32_u24_e32 v39, 0x110, v38
	v_lshlrev_b32_e32 v40, 4, v40
	v_and_b32_e32 v32, 0x180, v32
	v_add3_u32 v54, v39, v40, v20
	v_add_u16_e32 v20, s26, v37
	v_or3_b32 v32, v36, v32, v33
	v_and_b32_e32 v20, 0x7f, v20
	v_lshl_or_b32 v34, v32, 1, v34
	v_lshlrev_b32_e32 v32, 11, v38
	v_cndmask_b32_e64 v26, v48, 1.0, s[0:1]
	s_mov_b64 s[0:1], 0x1000
	v_lshl_or_b32 v55, v20, 6, v38
	v_lshl_or_b32 v20, v20, 17, v32
	v_lshl_add_u64 v[28:29], v[22:23], 0, s[0:1]
	s_mov_b64 s[0:1], 0x2000
	v_lshl_add_u64 v[32:33], v[34:35], 0, v[20:21]
	v_and_b32_e32 v42, 0xff, v46
	s_mov_b32 s2, 0
	v_lshl_add_u64 v[30:31], v[22:23], 0, s[0:1]
	v_mov_b32_e32 v27, v26
	v_lshl_add_u64 v[32:33], s[76:77], 0, v[32:33]
	global_load_dwordx4 v[94:97], v[22:23], off
	global_load_dwordx4 v[98:101], v[22:23], off offset:16
	global_load_dwordx4 v[102:105], v[28:29], off
	global_load_dwordx4 v[106:109], v[28:29], off offset:16
	global_load_dwordx4 v[110:113], v[30:31], off
	global_load_dwordx4 v[114:117], v[30:31], off offset:16
	s_movk_i32 s2, 0x800
	v_mov_b32_e32 v184, v55
	v_add_u32_e32 v185, -1, v184
	v_mov_b32_e32 v118, 0
	v_mov_b32_e32 v119, 0
	v_mov_b32_e32 v120, 0
	v_mov_b32_e32 v121, 0
	v_mov_b32_e32 v122, 0
	v_mov_b32_e32 v123, 0
	v_mov_b32_e32 v124, 0
	v_mov_b32_e32 v125, 0
	v_mov_b32_e32 v126, 0
	v_mov_b32_e32 v127, 0
	v_mov_b32_e32 v128, 0
	v_mov_b32_e32 v129, 0
	v_mad_i64_i32 v[186:187], s[0:1], v185, s2, v[18:19]
	v_cmp_lt_u32_e64 s[0:1], 2, v184
	s_and_saveexec_b64 s[4:5], s[0:1]
	global_load_dwordx4 v[118:121], v[186:187], off offset:-4096
	s_or_b64 exec, exec, s[4:5]
	v_cmp_lt_u32_e64 s[0:1], 1, v184
	s_and_saveexec_b64 s[4:5], s[0:1]
	global_load_dwordx4 v[122:125], v[186:187], off offset:-2048
	s_or_b64 exec, exec, s[4:5]
	v_cmp_ne_u32_e64 s[0:1], 0, v184
	s_and_saveexec_b64 s[4:5], s[0:1]
	global_load_dwordx4 v[126:129], v[186:187], off
	s_or_b64 exec, exec, s[4:5]
	global_load_dwordx4 v[130:133], v[186:187], off offset:2048
	v_add_u32_e32 v184, 8, v55
	v_add_u32_e32 v185, -1, v184
	v_mov_b32_e32 v134, 0
	v_mov_b32_e32 v135, 0
	v_mov_b32_e32 v136, 0
	v_mov_b32_e32 v137, 0
	v_mov_b32_e32 v138, 0
	v_mov_b32_e32 v139, 0
	v_mov_b32_e32 v140, 0
	v_mov_b32_e32 v141, 0
	v_mov_b32_e32 v142, 0
	v_mov_b32_e32 v143, 0
	v_mov_b32_e32 v144, 0
	v_mov_b32_e32 v145, 0
	v_mad_i64_i32 v[186:187], s[0:1], v185, s2, v[18:19]
	v_cmp_lt_u32_e64 s[0:1], 2, v184
	s_and_saveexec_b64 s[4:5], s[0:1]
	global_load_dwordx4 v[134:137], v[186:187], off offset:-4096
	s_or_b64 exec, exec, s[4:5]
	v_cmp_lt_u32_e64 s[0:1], 1, v184
	s_and_saveexec_b64 s[4:5], s[0:1]
	global_load_dwordx4 v[138:141], v[186:187], off offset:-2048
	s_or_b64 exec, exec, s[4:5]
	v_cmp_ne_u32_e64 s[0:1], 0, v184
	s_and_saveexec_b64 s[4:5], s[0:1]
	global_load_dwordx4 v[142:145], v[186:187], off
	s_or_b64 exec, exec, s[4:5]
	global_load_dwordx4 v[146:149], v[186:187], off offset:2048
	v_add_u32_e32 v184, 16, v55
	v_add_u32_e32 v185, -1, v184
	v_mov_b32_e32 v150, 0
	v_mov_b32_e32 v151, 0
	v_mov_b32_e32 v152, 0
	v_mov_b32_e32 v153, 0
	v_mov_b32_e32 v154, 0
	v_mov_b32_e32 v155, 0
	v_mov_b32_e32 v156, 0
	v_mov_b32_e32 v157, 0
	v_mov_b32_e32 v158, 0
	v_mov_b32_e32 v159, 0
	v_mov_b32_e32 v160, 0
	v_mov_b32_e32 v161, 0
	v_mad_i64_i32 v[186:187], s[0:1], v185, s2, v[18:19]
	v_cmp_lt_u32_e64 s[0:1], 2, v184
	s_and_saveexec_b64 s[4:5], s[0:1]
	global_load_dwordx4 v[150:153], v[186:187], off offset:-4096
	s_or_b64 exec, exec, s[4:5]
	v_cmp_lt_u32_e64 s[0:1], 1, v184
	s_and_saveexec_b64 s[4:5], s[0:1]
	global_load_dwordx4 v[154:157], v[186:187], off offset:-2048
	s_or_b64 exec, exec, s[4:5]
	v_cmp_ne_u32_e64 s[0:1], 0, v184
	s_and_saveexec_b64 s[4:5], s[0:1]
	global_load_dwordx4 v[158:161], v[186:187], off
	s_or_b64 exec, exec, s[4:5]
	global_load_dwordx4 v[162:165], v[186:187], off offset:2048
	v_add_u32_e32 v184, 24, v55
	v_add_u32_e32 v185, -1, v184
	v_mov_b32_e32 v166, 0
	v_mov_b32_e32 v167, 0
	v_mov_b32_e32 v168, 0
	v_mov_b32_e32 v169, 0
	v_mov_b32_e32 v170, 0
	v_mov_b32_e32 v171, 0
	v_mov_b32_e32 v172, 0
	v_mov_b32_e32 v173, 0
	v_mov_b32_e32 v174, 0
	v_mov_b32_e32 v175, 0
	v_mov_b32_e32 v176, 0
	v_mov_b32_e32 v177, 0
	v_mad_i64_i32 v[186:187], s[0:1], v185, s2, v[18:19]
	v_cmp_lt_u32_e64 s[0:1], 2, v184
	s_and_saveexec_b64 s[4:5], s[0:1]
	global_load_dwordx4 v[166:169], v[186:187], off offset:-4096
	s_or_b64 exec, exec, s[4:5]
	v_cmp_lt_u32_e64 s[0:1], 1, v184
	s_and_saveexec_b64 s[4:5], s[0:1]
	global_load_dwordx4 v[170:173], v[186:187], off offset:-2048
	s_or_b64 exec, exec, s[4:5]
	v_cmp_ne_u32_e64 s[0:1], 0, v184
	s_and_saveexec_b64 s[4:5], s[0:1]
	global_load_dwordx4 v[174:177], v[186:187], off
	s_or_b64 exec, exec, s[4:5]
	global_load_dwordx4 v[178:181], v[186:187], off offset:2048
	s_waitcnt vmcnt(12)
; DI unsigned pack2(float a, float b) { const f32x2 v = {a, b}; return __builtin_bit_cast(unsigned, __builtin_convertvector(v, bf16v2)); }
; DI void conv_unit(const u16* __restrict__ PM, const float* __restrict__ conv_w, const float* __restrict__ conv_b, int b, int sl0, int ch, float scale, float* a8) {
;   { const float4 b0 = *(const float4*)(conv_b + ch), b1 = *(const float4*)(conv_b + ch + 4); a8[0] = b0.x; a8[1] = b0.y; a8[2] = b0.z; a8[3] = b0.w; a8[4] = b1.x; a8[5] = b1.y; a8[6] = b1.z; a8[7] = b1.w; }
; #pragma unroll
;   for (int j = 0; j < 4; ++j) {
;     const int sl = sl0 - 3 + j;
;     if (sl >= 0) {
;       const uint4 raw = *(const uint4*)(PM + ((size_t)b * SEQ + sl) * 1024 + ch);
;       float x8[8]; unpack8(raw, x8);
;       const float4 w0 = *(const float4*)(conv_w + j * 1024 + ch), w1 = *(const float4*)(conv_w + j * 1024 + ch + 4);
;       a8[0] += w0.x * x8[0]; a8[1] += w0.y * x8[1]; a8[2] += w0.z * x8[2]; a8[3] += w0.w * x8[3];
;       a8[4] += w1.x * x8[4]; a8[5] += w1.y * x8[5]; a8[6] += w1.z * x8[6]; a8[7] += w1.w * x8[7];
;     }
;   }
; #pragma unroll
;   for (int e = 0; e < 8; ++e) { const float v = a8[e]; a8[e] = scale * v * __builtin_amdgcn_rcpf(1.f + __expf(-v)); }
; }
; DI void mlstmC_pair(const Params& p, char* lds_all, int pair) {
;     ...
;   for (int i = 0; i < 8; ++i) {
;     const int cg8 = ltid & 31, isK = cg8 >> 4, chl = (cg8 & 15) * 8, t = (ltid >> 5) + 8 * i;
;     float a8[8];
;     conv_unit(PM, p.in[5], p.in[6], b, c * 64 + t, (isK ? 512 : 0) + hd * 128 + chl, isK ? 0.08838834764831845f : 1.f, a8);
;     uint4 o; o.x = pack2(a8[0], a8[1]); o.y = pack2(a8[2], a8[3]); o.z = pack2(a8[4], a8[5]); o.w = pack2(a8[6], a8[7]);
;     *(uint4*)((isK ? Ks : Qs) + t * 136 + chl) = o;
	v_lshlrev_b32_e32 v188, 16, v118
	v_and_b32_e32 v189, 0xffff0000, v118
	v_lshlrev_b32_e32 v190, 16, v119
	v_and_b32_e32 v191, 0xffff0000, v119
	v_lshlrev_b32_e32 v192, 16, v120
	v_and_b32_e32 v193, 0xffff0000, v120
	v_lshlrev_b32_e32 v194, 16, v121
	v_and_b32_e32 v195, 0xffff0000, v121
	v_pk_fma_f32 v[204:205], v[94:95], v[188:189], v[4:5]
	v_pk_fma_f32 v[206:207], v[96:97], v[190:191], v[6:7]
	v_pk_fma_f32 v[208:209], v[98:99], v[192:193], v[0:1]
	v_pk_fma_f32 v[210:211], v[100:101], v[194:195], v[2:3]
	v_lshlrev_b32_e32 v188, 16, v122
	v_and_b32_e32 v189, 0xffff0000, v122
	v_lshlrev_b32_e32 v190, 16, v123
	v_and_b32_e32 v191, 0xffff0000, v123
	v_lshlrev_b32_e32 v192, 16, v124
	v_and_b32_e32 v193, 0xffff0000, v124
	v_lshlrev_b32_e32 v194, 16, v125
	v_and_b32_e32 v195, 0xffff0000, v125
	v_pk_fma_f32 v[204:205], v[102:103], v[188:189], v[204:205]
	v_pk_fma_f32 v[206:207], v[104:105], v[190:191], v[206:207]
	v_pk_fma_f32 v[208:209], v[106:107], v[192:193], v[208:209]
	v_pk_fma_f32 v[210:211], v[108:109], v[194:195], v[210:211]
	v_lshlrev_b32_e32 v188, 16, v126
	v_and_b32_e32 v189, 0xffff0000, v126
	v_lshlrev_b32_e32 v190, 16, v127
	v_and_b32_e32 v191, 0xffff0000, v127
	v_lshlrev_b32_e32 v192, 16, v128
	v_and_b32_e32 v193, 0xffff0000, v128
	v_lshlrev_b32_e32 v194, 16, v129
	v_and_b32_e32 v195, 0xffff0000, v129
	v_pk_fma_f32 v[204:205], v[110:111], v[188:189], v[204:205]
	v_pk_fma_f32 v[206:207], v[112:113], v[190:191], v[206:207]
	v_pk_fma_f32 v[208:209], v[114:115], v[192:193], v[208:209]
	v_pk_fma_f32 v[210:211], v[116:117], v[194:195], v[210:211]
	v_lshlrev_b32_e32 v188, 16, v130
	v_and_b32_e32 v189, 0xffff0000, v130
	v_lshlrev_b32_e32 v190, 16, v131
	v_and_b32_e32 v191, 0xffff0000, v131
	v_lshlrev_b32_e32 v192, 16, v132
	v_and_b32_e32 v193, 0xffff0000, v132
	v_lshlrev_b32_e32 v194, 16, v133
	v_and_b32_e32 v195, 0xffff0000, v133
	v_pk_fma_f32 v[204:205], v[8:9], v[188:189], v[204:205]
	v_pk_fma_f32 v[206:207], v[10:11], v[190:191], v[206:207]
	v_pk_fma_f32 v[208:209], v[12:13], v[192:193], v[208:209]
	v_pk_fma_f32 v[210:211], v[14:15], v[194:195], v[210:211]
	v_mul_f32_e32 v212, 0xbfb8aa3b, v204
	v_mul_f32_e32 v213, 0xbfb8aa3b, v205
	v_mul_f32_e32 v214, 0xbfb8aa3b, v206
	v_mul_f32_e32 v215, 0xbfb8aa3b, v207
	v_mul_f32_e32 v216, 0xbfb8aa3b, v208
	v_mul_f32_e32 v217, 0xbfb8aa3b, v209
	v_mul_f32_e32 v218, 0xbfb8aa3b, v210
	v_mul_f32_e32 v219, 0xbfb8aa3b, v211
	v_pk_mul_f32 v[188:189], v[26:27], v[204:205]
	v_pk_mul_f32 v[190:191], v[26:27], v[206:207]
	v_pk_mul_f32 v[192:193], v[26:27], v[208:209]
	v_pk_mul_f32 v[194:195], v[26:27], v[210:211]
	v_exp_f32_e32 v212, v212
	v_exp_f32_e32 v213, v213
	v_exp_f32_e32 v214, v214
	v_exp_f32_e32 v215, v215
	v_exp_f32_e32 v216, v216
	v_exp_f32_e32 v217, v217
	v_exp_f32_e32 v218, v218
	v_exp_f32_e32 v219, v219
	v_add_f32_e32 v212, 1.0, v212
	v_add_f32_e32 v213, 1.0, v213
	v_add_f32_e32 v214, 1.0, v214
	v_add_f32_e32 v215, 1.0, v215
	v_add_f32_e32 v216, 1.0, v216
	v_add_f32_e32 v217, 1.0, v217
	v_add_f32_e32 v218, 1.0, v218
	v_add_f32_e32 v219, 1.0, v219
	v_rcp_f32_e32 v212, v212
	v_rcp_f32_e32 v213, v213
	v_rcp_f32_e32 v214, v214
	v_rcp_f32_e32 v215, v215
	v_rcp_f32_e32 v216, v216
	v_rcp_f32_e32 v217, v217
	v_rcp_f32_e32 v218, v218
	v_rcp_f32_e32 v219, v219
	v_pk_mul_f32 v[188:189], v[188:189], v[212:213]
	v_pk_mul_f32 v[190:191], v[190:191], v[214:215]
	v_pk_mul_f32 v[192:193], v[192:193], v[216:217]
	v_pk_mul_f32 v[194:195], v[194:195], v[218:219]
	v_cvt_pk_bf16_f32 v196, v188, v189
	v_cvt_pk_bf16_f32 v197, v190, v191
	v_cvt_pk_bf16_f32 v198, v192, v193
	v_cvt_pk_bf16_f32 v199, v194, v195
	ds_write_b128 v54, v[196:199]
	v_add_u32_e32 v184, 32, v55
	v_add_u32_e32 v185, -1, v184
	v_mov_b32_e32 v118, 0
	v_mov_b32_e32 v119, 0
	v_mov_b32_e32 v120, 0
	v_mov_b32_e32 v121, 0
	v_mov_b32_e32 v122, 0
	v_mov_b32_e32 v123, 0
	v_mov_b32_e32 v124, 0
	v_mov_b32_e32 v125, 0
	v_mov_b32_e32 v126, 0
	v_mov_b32_e32 v127, 0
	v_mov_b32_e32 v128, 0
	v_mov_b32_e32 v129, 0
	v_mad_i64_i32 v[186:187], s[0:1], v185, s2, v[18:19]
	v_cmp_lt_u32_e64 s[0:1], 2, v184
	s_and_saveexec_b64 s[4:5], s[0:1]
	global_load_dwordx4 v[118:121], v[186:187], off offset:-4096
	s_or_b64 exec, exec, s[4:5]
	v_cmp_lt_u32_e64 s[0:1], 1, v184
	s_and_saveexec_b64 s[4:5], s[0:1]
	global_load_dwordx4 v[122:125], v[186:187], off offset:-2048
	s_or_b64 exec, exec, s[4:5]
	v_cmp_ne_u32_e64 s[0:1], 0, v184
	s_and_saveexec_b64 s[4:5], s[0:1]
	global_load_dwordx4 v[126:129], v[186:187], off
	s_or_b64 exec, exec, s[4:5]
	global_load_dwordx4 v[130:133], v[186:187], off offset:2048
	s_waitcnt vmcnt(12)
; DI unsigned pack2(float a, float b) { const f32x2 v = {a, b}; return __builtin_bit_cast(unsigned, __builtin_convertvector(v, bf16v2)); }
; DI void conv_unit(const u16* __restrict__ PM, const float* __restrict__ conv_w, const float* __restrict__ conv_b, int b, int sl0, int ch, float scale, float* a8) {
;   { const float4 b0 = *(const float4*)(conv_b + ch), b1 = *(const float4*)(conv_b + ch + 4); a8[0] = b0.x; a8[1] = b0.y; a8[2] = b0.z; a8[3] = b0.w; a8[4] = b1.x; a8[5] = b1.y; a8[6] = b1.z; a8[7] = b1.w; }
; #pragma unroll
;   for (int j = 0; j < 4; ++j) {
;     const int sl = sl0 - 3 + j;
;     if (sl >= 0) {
;       const uint4 raw = *(const uint4*)(PM + ((size_t)b * SEQ + sl) * 1024 + ch);
;       float x8[8]; unpack8(raw, x8);
;       const float4 w0 = *(const float4*)(conv_w + j * 1024 + ch), w1 = *(const float4*)(conv_w + j * 1024 + ch + 4);
;       a8[0] += w0.x * x8[0]; a8[1] += w0.y * x8[1]; a8[2] += w0.z * x8[2]; a8[3] += w0.w * x8[3];
;       a8[4] += w1.x * x8[4]; a8[5] += w1.y * x8[5]; a8[6] += w1.z * x8[6]; a8[7] += w1.w * x8[7];
;     }
;   }
; #pragma unroll
;   for (int e = 0; e < 8; ++e) { const float v = a8[e]; a8[e] = scale * v * __builtin_amdgcn_rcpf(1.f + __expf(-v)); }
; }
; DI void mlstmC_pair(const Params& p, char* lds_all, int pair) {
;     ...
;   for (int i = 0; i < 8; ++i) {
;     const int cg8 = ltid & 31, isK = cg8 >> 4, chl = (cg8 & 15) * 8, t = (ltid >> 5) + 8 * i;
;     float a8[8];
;     conv_unit(PM, p.in[5], p.in[6], b, c * 64 + t, (isK ? 512 : 0) + hd * 128 + chl, isK ? 0.08838834764831845f : 1.f, a8);
;     uint4 o; o.x = pack2(a8[0], a8[1]); o.y = pack2(a8[2], a8[3]); o.z = pack2(a8[4], a8[5]); o.w = pack2(a8[6], a8[7]);
;     *(uint4*)((isK ? Ks : Qs) + t * 136 + chl) = o;
	v_lshlrev_b32_e32 v188, 16, v134
	v_and_b32_e32 v189, 0xffff0000, v134
	v_lshlrev_b32_e32 v190, 16, v135
	v_and_b32_e32 v191, 0xffff0000, v135
	v_lshlrev_b32_e32 v192, 16, v136
	v_and_b32_e32 v193, 0xffff0000, v136
	v_lshlrev_b32_e32 v194, 16, v137
	v_and_b32_e32 v195, 0xffff0000, v137
	v_pk_fma_f32 v[204:205], v[94:95], v[188:189], v[4:5]
	v_pk_fma_f32 v[206:207], v[96:97], v[190:191], v[6:7]
	v_pk_fma_f32 v[208:209], v[98:99], v[192:193], v[0:1]
	v_pk_fma_f32 v[210:211], v[100:101], v[194:195], v[2:3]
	v_lshlrev_b32_e32 v188, 16, v138
	v_and_b32_e32 v189, 0xffff0000, v138
	v_lshlrev_b32_e32 v190, 16, v139
	v_and_b32_e32 v191, 0xffff0000, v139
	v_lshlrev_b32_e32 v192, 16, v140
	v_and_b32_e32 v193, 0xffff0000, v140
	v_lshlrev_b32_e32 v194, 16, v141
	v_and_b32_e32 v195, 0xffff0000, v141
	v_pk_fma_f32 v[204:205], v[102:103], v[188:189], v[204:205]
	v_pk_fma_f32 v[206:207], v[104:105], v[190:191], v[206:207]
	v_pk_fma_f32 v[208:209], v[106:107], v[192:193], v[208:209]
	v_pk_fma_f32 v[210:211], v[108:109], v[194:195], v[210:211]
	v_lshlrev_b32_e32 v188, 16, v142
	v_and_b32_e32 v189, 0xffff0000, v142
	v_lshlrev_b32_e32 v190, 16, v143
	v_and_b32_e32 v191, 0xffff0000, v143
	v_lshlrev_b32_e32 v192, 16, v144
	v_and_b32_e32 v193, 0xffff0000, v144
	v_lshlrev_b32_e32 v194, 16, v145
	v_and_b32_e32 v195, 0xffff0000, v145
	v_pk_fma_f32 v[204:205], v[110:111], v[188:189], v[204:205]
	v_pk_fma_f32 v[206:207], v[112:113], v[190:191], v[206:207]
	v_pk_fma_f32 v[208:209], v[114:115], v[192:193], v[208:209]
	v_pk_fma_f32 v[210:211], v[116:117], v[194:195], v[210:211]
	v_lshlrev_b32_e32 v188, 16, v146
	v_and_b32_e32 v189, 0xffff0000, v146
	v_lshlrev_b32_e32 v190, 16, v147
	v_and_b32_e32 v191, 0xffff0000, v147
	v_lshlrev_b32_e32 v192, 16, v148
	v_and_b32_e32 v193, 0xffff0000, v148
	v_lshlrev_b32_e32 v194, 16, v149
	v_and_b32_e32 v195, 0xffff0000, v149
	v_pk_fma_f32 v[204:205], v[8:9], v[188:189], v[204:205]
	v_pk_fma_f32 v[206:207], v[10:11], v[190:191], v[206:207]
	v_pk_fma_f32 v[208:209], v[12:13], v[192:193], v[208:209]
	v_pk_fma_f32 v[210:211], v[14:15], v[194:195], v[210:211]
	v_mul_f32_e32 v212, 0xbfb8aa3b, v204
	v_mul_f32_e32 v213, 0xbfb8aa3b, v205
	v_mul_f32_e32 v214, 0xbfb8aa3b, v206
	v_mul_f32_e32 v215, 0xbfb8aa3b, v207
	v_mul_f32_e32 v216, 0xbfb8aa3b, v208
	v_mul_f32_e32 v217, 0xbfb8aa3b, v209
	v_mul_f32_e32 v218, 0xbfb8aa3b, v210
	v_mul_f32_e32 v219, 0xbfb8aa3b, v211
	v_pk_mul_f32 v[188:189], v[26:27], v[204:205]
	v_pk_mul_f32 v[190:191], v[26:27], v[206:207]
	v_pk_mul_f32 v[192:193], v[26:27], v[208:209]
	v_pk_mul_f32 v[194:195], v[26:27], v[210:211]
	v_exp_f32_e32 v212, v212
	v_exp_f32_e32 v213, v213
	v_exp_f32_e32 v214, v214
	v_exp_f32_e32 v215, v215
	v_exp_f32_e32 v216, v216
	v_exp_f32_e32 v217, v217
	v_exp_f32_e32 v218, v218
	v_exp_f32_e32 v219, v219
	v_add_f32_e32 v212, 1.0, v212
	v_add_f32_e32 v213, 1.0, v213
	v_add_f32_e32 v214, 1.0, v214
	v_add_f32_e32 v215, 1.0, v215
	v_add_f32_e32 v216, 1.0, v216
	v_add_f32_e32 v217, 1.0, v217
	v_add_f32_e32 v218, 1.0, v218
	v_add_f32_e32 v219, 1.0, v219
	v_rcp_f32_e32 v212, v212
	v_rcp_f32_e32 v213, v213
	v_rcp_f32_e32 v214, v214
	v_rcp_f32_e32 v215, v215
	v_rcp_f32_e32 v216, v216
	v_rcp_f32_e32 v217, v217
	v_rcp_f32_e32 v218, v218
	v_rcp_f32_e32 v219, v219
	v_pk_mul_f32 v[188:189], v[188:189], v[212:213]
	v_pk_mul_f32 v[190:191], v[190:191], v[214:215]
	v_pk_mul_f32 v[192:193], v[192:193], v[216:217]
	v_pk_mul_f32 v[194:195], v[194:195], v[218:219]
	v_cvt_pk_bf16_f32 v196, v188, v189
	v_cvt_pk_bf16_f32 v197, v190, v191
	v_cvt_pk_bf16_f32 v198, v192, v193
	v_cvt_pk_bf16_f32 v199, v194, v195
	ds_write_b128 v54, v[196:199] offset:2176
	v_add_u32_e32 v184, 40, v55
	v_add_u32_e32 v185, -1, v184
	v_mov_b32_e32 v134, 0
	v_mov_b32_e32 v135, 0
	v_mov_b32_e32 v136, 0
	v_mov_b32_e32 v137, 0
	v_mov_b32_e32 v138, 0
	v_mov_b32_e32 v139, 0
	v_mov_b32_e32 v140, 0
	v_mov_b32_e32 v141, 0
	v_mov_b32_e32 v142, 0
	v_mov_b32_e32 v143, 0
	v_mov_b32_e32 v144, 0
	v_mov_b32_e32 v145, 0
	v_mad_i64_i32 v[186:187], s[0:1], v185, s2, v[18:19]
	v_cmp_lt_u32_e64 s[0:1], 2, v184
	s_and_saveexec_b64 s[4:5], s[0:1]
	global_load_dwordx4 v[134:137], v[186:187], off offset:-4096
	s_or_b64 exec, exec, s[4:5]
	v_cmp_lt_u32_e64 s[0:1], 1, v184
	s_and_saveexec_b64 s[4:5], s[0:1]
	global_load_dwordx4 v[138:141], v[186:187], off offset:-2048
	s_or_b64 exec, exec, s[4:5]
	v_cmp_ne_u32_e64 s[0:1], 0, v184
	s_and_saveexec_b64 s[4:5], s[0:1]
	global_load_dwordx4 v[142:145], v[186:187], off
	s_or_b64 exec, exec, s[4:5]
	global_load_dwordx4 v[146:149], v[186:187], off offset:2048
	s_waitcnt vmcnt(12)
; DI unsigned pack2(float a, float b) { const f32x2 v = {a, b}; return __builtin_bit_cast(unsigned, __builtin_convertvector(v, bf16v2)); }
; DI void conv_unit(const u16* __restrict__ PM, const float* __restrict__ conv_w, const float* __restrict__ conv_b, int b, int sl0, int ch, float scale, float* a8) {
;   { const float4 b0 = *(const float4*)(conv_b + ch), b1 = *(const float4*)(conv_b + ch + 4); a8[0] = b0.x; a8[1] = b0.y; a8[2] = b0.z; a8[3] = b0.w; a8[4] = b1.x; a8[5] = b1.y; a8[6] = b1.z; a8[7] = b1.w; }
; #pragma unroll
;   for (int j = 0; j < 4; ++j) {
;     const int sl = sl0 - 3 + j;
;     if (sl >= 0) {
;       const uint4 raw = *(const uint4*)(PM + ((size_t)b * SEQ + sl) * 1024 + ch);
;       float x8[8]; unpack8(raw, x8);
;       const float4 w0 = *(const float4*)(conv_w + j * 1024 + ch), w1 = *(const float4*)(conv_w + j * 1024 + ch + 4);
;       a8[0] += w0.x * x8[0]; a8[1] += w0.y * x8[1]; a8[2] += w0.z * x8[2]; a8[3] += w0.w * x8[3];
;       a8[4] += w1.x * x8[4]; a8[5] += w1.y * x8[5]; a8[6] += w1.z * x8[6]; a8[7] += w1.w * x8[7];
;     }
;   }
; #pragma unroll
;   for (int e = 0; e < 8; ++e) { const float v = a8[e]; a8[e] = scale * v * __builtin_amdgcn_rcpf(1.f + __expf(-v)); }
; }
; DI void mlstmC_pair(const Params& p, char* lds_all, int pair) {
;     ...
;   for (int i = 0; i < 8; ++i) {
;     const int cg8 = ltid & 31, isK = cg8 >> 4, chl = (cg8 & 15) * 8, t = (ltid >> 5) + 8 * i;
;     float a8[8];
;     conv_unit(PM, p.in[5], p.in[6], b, c * 64 + t, (isK ? 512 : 0) + hd * 128 + chl, isK ? 0.08838834764831845f : 1.f, a8);
;     uint4 o; o.x = pack2(a8[0], a8[1]); o.y = pack2(a8[2], a8[3]); o.z = pack2(a8[4], a8[5]); o.w = pack2(a8[6], a8[7]);
;     *(uint4*)((isK ? Ks : Qs) + t * 136 + chl) = o;
	v_lshlrev_b32_e32 v188, 16, v150
	v_and_b32_e32 v189, 0xffff0000, v150
	v_lshlrev_b32_e32 v190, 16, v151
	v_and_b32_e32 v191, 0xffff0000, v151
	v_lshlrev_b32_e32 v192, 16, v152
	v_and_b32_e32 v193, 0xffff0000, v152
	v_lshlrev_b32_e32 v194, 16, v153
	v_and_b32_e32 v195, 0xffff0000, v153
	v_pk_fma_f32 v[204:205], v[94:95], v[188:189], v[4:5]
	v_pk_fma_f32 v[206:207], v[96:97], v[190:191], v[6:7]
	v_pk_fma_f32 v[208:209], v[98:99], v[192:193], v[0:1]
	v_pk_fma_f32 v[210:211], v[100:101], v[194:195], v[2:3]
	v_lshlrev_b32_e32 v188, 16, v154
	v_and_b32_e32 v189, 0xffff0000, v154
	v_lshlrev_b32_e32 v190, 16, v155
	v_and_b32_e32 v191, 0xffff0000, v155
	v_lshlrev_b32_e32 v192, 16, v156
	v_and_b32_e32 v193, 0xffff0000, v156
	v_lshlrev_b32_e32 v194, 16, v157
	v_and_b32_e32 v195, 0xffff0000, v157
	v_pk_fma_f32 v[204:205], v[102:103], v[188:189], v[204:205]
	v_pk_fma_f32 v[206:207], v[104:105], v[190:191], v[206:207]
	v_pk_fma_f32 v[208:209], v[106:107], v[192:193], v[208:209]
	v_pk_fma_f32 v[210:211], v[108:109], v[194:195], v[210:211]
	v_lshlrev_b32_e32 v188, 16, v158
	v_and_b32_e32 v189, 0xffff0000, v158
	v_lshlrev_b32_e32 v190, 16, v159
	v_and_b32_e32 v191, 0xffff0000, v159
	v_lshlrev_b32_e32 v192, 16, v160
	v_and_b32_e32 v193, 0xffff0000, v160
	v_lshlrev_b32_e32 v194, 16, v161
	v_and_b32_e32 v195, 0xffff0000, v161
	v_pk_fma_f32 v[204:205], v[110:111], v[188:189], v[204:205]
	v_pk_fma_f32 v[206:207], v[112:113], v[190:191], v[206:207]
	v_pk_fma_f32 v[208:209], v[114:115], v[192:193], v[208:209]
	v_pk_fma_f32 v[210:211], v[116:117], v[194:195], v[210:211]
	v_lshlrev_b32_e32 v188, 16, v162
	v_and_b32_e32 v189, 0xffff0000, v162
	v_lshlrev_b32_e32 v190, 16, v163
	v_and_b32_e32 v191, 0xffff0000, v163
	v_lshlrev_b32_e32 v192, 16, v164
	v_and_b32_e32 v193, 0xffff0000, v164
	v_lshlrev_b32_e32 v194, 16, v165
	v_and_b32_e32 v195, 0xffff0000, v165
	v_pk_fma_f32 v[204:205], v[8:9], v[188:189], v[204:205]
	v_pk_fma_f32 v[206:207], v[10:11], v[190:191], v[206:207]
	v_pk_fma_f32 v[208:209], v[12:13], v[192:193], v[208:209]
	v_pk_fma_f32 v[210:211], v[14:15], v[194:195], v[210:211]
	v_mul_f32_e32 v212, 0xbfb8aa3b, v204
	v_mul_f32_e32 v213, 0xbfb8aa3b, v205
	v_mul_f32_e32 v214, 0xbfb8aa3b, v206
	v_mul_f32_e32 v215, 0xbfb8aa3b, v207
	v_mul_f32_e32 v216, 0xbfb8aa3b, v208
	v_mul_f32_e32 v217, 0xbfb8aa3b, v209
	v_mul_f32_e32 v218, 0xbfb8aa3b, v210
	v_mul_f32_e32 v219, 0xbfb8aa3b, v211
	v_pk_mul_f32 v[188:189], v[26:27], v[204:205]
	v_pk_mul_f32 v[190:191], v[26:27], v[206:207]
	v_pk_mul_f32 v[192:193], v[26:27], v[208:209]
	v_pk_mul_f32 v[194:195], v[26:27], v[210:211]
	v_exp_f32_e32 v212, v212
	v_exp_f32_e32 v213, v213
	v_exp_f32_e32 v214, v214
	v_exp_f32_e32 v215, v215
	v_exp_f32_e32 v216, v216
	v_exp_f32_e32 v217, v217
	v_exp_f32_e32 v218, v218
	v_exp_f32_e32 v219, v219
	v_add_f32_e32 v212, 1.0, v212
	v_add_f32_e32 v213, 1.0, v213
	v_add_f32_e32 v214, 1.0, v214
	v_add_f32_e32 v215, 1.0, v215
	v_add_f32_e32 v216, 1.0, v216
	v_add_f32_e32 v217, 1.0, v217
	v_add_f32_e32 v218, 1.0, v218
	v_add_f32_e32 v219, 1.0, v219
	v_rcp_f32_e32 v212, v212
	v_rcp_f32_e32 v213, v213
	v_rcp_f32_e32 v214, v214
	v_rcp_f32_e32 v215, v215
	v_rcp_f32_e32 v216, v216
	v_rcp_f32_e32 v217, v217
	v_rcp_f32_e32 v218, v218
	v_rcp_f32_e32 v219, v219
	v_pk_mul_f32 v[188:189], v[188:189], v[212:213]
	v_pk_mul_f32 v[190:191], v[190:191], v[214:215]
	v_pk_mul_f32 v[192:193], v[192:193], v[216:217]
	v_pk_mul_f32 v[194:195], v[194:195], v[218:219]
	v_cvt_pk_bf16_f32 v196, v188, v189
	v_cvt_pk_bf16_f32 v197, v190, v191
	v_cvt_pk_bf16_f32 v198, v192, v193
	v_cvt_pk_bf16_f32 v199, v194, v195
	ds_write_b128 v54, v[196:199] offset:4352
	v_add_u32_e32 v184, 48, v55
	v_add_u32_e32 v185, -1, v184
	v_mov_b32_e32 v150, 0
	v_mov_b32_e32 v151, 0
	v_mov_b32_e32 v152, 0
	v_mov_b32_e32 v153, 0
	v_mov_b32_e32 v154, 0
	v_mov_b32_e32 v155, 0
	v_mov_b32_e32 v156, 0
	v_mov_b32_e32 v157, 0
	v_mov_b32_e32 v158, 0
	v_mov_b32_e32 v159, 0
	v_mov_b32_e32 v160, 0
	v_mov_b32_e32 v161, 0
	v_mad_i64_i32 v[186:187], s[0:1], v185, s2, v[18:19]
	v_cmp_lt_u32_e64 s[0:1], 2, v184
	s_and_saveexec_b64 s[4:5], s[0:1]
	global_load_dwordx4 v[150:153], v[186:187], off offset:-4096
	s_or_b64 exec, exec, s[4:5]
	v_cmp_lt_u32_e64 s[0:1], 1, v184
	s_and_saveexec_b64 s[4:5], s[0:1]
	global_load_dwordx4 v[154:157], v[186:187], off offset:-2048
	s_or_b64 exec, exec, s[4:5]
	v_cmp_ne_u32_e64 s[0:1], 0, v184
	s_and_saveexec_b64 s[4:5], s[0:1]
	global_load_dwordx4 v[158:161], v[186:187], off
	s_or_b64 exec, exec, s[4:5]
	global_load_dwordx4 v[162:165], v[186:187], off offset:2048
	s_waitcnt vmcnt(12)
; DI unsigned pack2(float a, float b) { const f32x2 v = {a, b}; return __builtin_bit_cast(unsigned, __builtin_convertvector(v, bf16v2)); }
; DI void conv_unit(const u16* __restrict__ PM, const float* __restrict__ conv_w, const float* __restrict__ conv_b, int b, int sl0, int ch, float scale, float* a8) {
;   { const float4 b0 = *(const float4*)(conv_b + ch), b1 = *(const float4*)(conv_b + ch + 4); a8[0] = b0.x; a8[1] = b0.y; a8[2] = b0.z; a8[3] = b0.w; a8[4] = b1.x; a8[5] = b1.y; a8[6] = b1.z; a8[7] = b1.w; }
; #pragma unroll
;   for (int j = 0; j < 4; ++j) {
;     const int sl = sl0 - 3 + j;
;     if (sl >= 0) {
;       const uint4 raw = *(const uint4*)(PM + ((size_t)b * SEQ + sl) * 1024 + ch);
;       float x8[8]; unpack8(raw, x8);
;       const float4 w0 = *(const float4*)(conv_w + j * 1024 + ch), w1 = *(const float4*)(conv_w + j * 1024 + ch + 4);
;       a8[0] += w0.x * x8[0]; a8[1] += w0.y * x8[1]; a8[2] += w0.z * x8[2]; a8[3] += w0.w * x8[3];
;       a8[4] += w1.x * x8[4]; a8[5] += w1.y * x8[5]; a8[6] += w1.z * x8[6]; a8[7] += w1.w * x8[7];
;     }
;   }
; #pragma unroll
;   for (int e = 0; e < 8; ++e) { const float v = a8[e]; a8[e] = scale * v * __builtin_amdgcn_rcpf(1.f + __expf(-v)); }
; }
; DI void mlstmC_pair(const Params& p, char* lds_all, int pair) {
;     ...
;   for (int i = 0; i < 8; ++i) {
;     const int cg8 = ltid & 31, isK = cg8 >> 4, chl = (cg8 & 15) * 8, t = (ltid >> 5) + 8 * i;
;     float a8[8];
;     conv_unit(PM, p.in[5], p.in[6], b, c * 64 + t, (isK ? 512 : 0) + hd * 128 + chl, isK ? 0.08838834764831845f : 1.f, a8);
;     uint4 o; o.x = pack2(a8[0], a8[1]); o.y = pack2(a8[2], a8[3]); o.z = pack2(a8[4], a8[5]); o.w = pack2(a8[6], a8[7]);
;     *(uint4*)((isK ? Ks : Qs) + t * 136 + chl) = o;
	v_lshlrev_b32_e32 v188, 16, v166
	v_and_b32_e32 v189, 0xffff0000, v166
	v_lshlrev_b32_e32 v190, 16, v167
	v_and_b32_e32 v191, 0xffff0000, v167
	v_lshlrev_b32_e32 v192, 16, v168
	v_and_b32_e32 v193, 0xffff0000, v168
	v_lshlrev_b32_e32 v194, 16, v169
	v_and_b32_e32 v195, 0xffff0000, v169
	v_pk_fma_f32 v[204:205], v[94:95], v[188:189], v[4:5]
	v_pk_fma_f32 v[206:207], v[96:97], v[190:191], v[6:7]
	v_pk_fma_f32 v[208:209], v[98:99], v[192:193], v[0:1]
	v_pk_fma_f32 v[210:211], v[100:101], v[194:195], v[2:3]
	v_lshlrev_b32_e32 v188, 16, v170
	v_and_b32_e32 v189, 0xffff0000, v170
	v_lshlrev_b32_e32 v190, 16, v171
	v_and_b32_e32 v191, 0xffff0000, v171
	v_lshlrev_b32_e32 v192, 16, v172
	v_and_b32_e32 v193, 0xffff0000, v172
	v_lshlrev_b32_e32 v194, 16, v173
	v_and_b32_e32 v195, 0xffff0000, v173
	v_pk_fma_f32 v[204:205], v[102:103], v[188:189], v[204:205]
	v_pk_fma_f32 v[206:207], v[104:105], v[190:191], v[206:207]
	v_pk_fma_f32 v[208:209], v[106:107], v[192:193], v[208:209]
	v_pk_fma_f32 v[210:211], v[108:109], v[194:195], v[210:211]
	v_lshlrev_b32_e32 v188, 16, v174
	v_and_b32_e32 v189, 0xffff0000, v174
	v_lshlrev_b32_e32 v190, 16, v175
	v_and_b32_e32 v191, 0xffff0000, v175
	v_lshlrev_b32_e32 v192, 16, v176
	v_and_b32_e32 v193, 0xffff0000, v176
	v_lshlrev_b32_e32 v194, 16, v177
	v_and_b32_e32 v195, 0xffff0000, v177
	v_pk_fma_f32 v[204:205], v[110:111], v[188:189], v[204:205]
	v_pk_fma_f32 v[206:207], v[112:113], v[190:191], v[206:207]
	v_pk_fma_f32 v[208:209], v[114:115], v[192:193], v[208:209]
	v_pk_fma_f32 v[210:211], v[116:117], v[194:195], v[210:211]
	v_lshlrev_b32_e32 v188, 16, v178
	v_and_b32_e32 v189, 0xffff0000, v178
	v_lshlrev_b32_e32 v190, 16, v179
	v_and_b32_e32 v191, 0xffff0000, v179
	v_lshlrev_b32_e32 v192, 16, v180
	v_and_b32_e32 v193, 0xffff0000, v180
	v_lshlrev_b32_e32 v194, 16, v181
	v_and_b32_e32 v195, 0xffff0000, v181
	v_pk_fma_f32 v[204:205], v[8:9], v[188:189], v[204:205]
	v_pk_fma_f32 v[206:207], v[10:11], v[190:191], v[206:207]
	v_pk_fma_f32 v[208:209], v[12:13], v[192:193], v[208:209]
	v_pk_fma_f32 v[210:211], v[14:15], v[194:195], v[210:211]
	v_mul_f32_e32 v212, 0xbfb8aa3b, v204
	v_mul_f32_e32 v213, 0xbfb8aa3b, v205
	v_mul_f32_e32 v214, 0xbfb8aa3b, v206
	v_mul_f32_e32 v215, 0xbfb8aa3b, v207
	v_mul_f32_e32 v216, 0xbfb8aa3b, v208
	v_mul_f32_e32 v217, 0xbfb8aa3b, v209
	v_mul_f32_e32 v218, 0xbfb8aa3b, v210
	v_mul_f32_e32 v219, 0xbfb8aa3b, v211
	v_pk_mul_f32 v[188:189], v[26:27], v[204:205]
	v_pk_mul_f32 v[190:191], v[26:27], v[206:207]
	v_pk_mul_f32 v[192:193], v[26:27], v[208:209]
	v_pk_mul_f32 v[194:195], v[26:27], v[210:211]
	v_exp_f32_e32 v212, v212
	v_exp_f32_e32 v213, v213
	v_exp_f32_e32 v214, v214
	v_exp_f32_e32 v215, v215
	v_exp_f32_e32 v216, v216
	v_exp_f32_e32 v217, v217
	v_exp_f32_e32 v218, v218
	v_exp_f32_e32 v219, v219
	v_add_f32_e32 v212, 1.0, v212
	v_add_f32_e32 v213, 1.0, v213
	v_add_f32_e32 v214, 1.0, v214
	v_add_f32_e32 v215, 1.0, v215
	v_add_f32_e32 v216, 1.0, v216
	v_add_f32_e32 v217, 1.0, v217
	v_add_f32_e32 v218, 1.0, v218
	v_add_f32_e32 v219, 1.0, v219
	v_rcp_f32_e32 v212, v212
	v_rcp_f32_e32 v213, v213
	v_rcp_f32_e32 v214, v214
	v_rcp_f32_e32 v215, v215
	v_rcp_f32_e32 v216, v216
	v_rcp_f32_e32 v217, v217
	v_rcp_f32_e32 v218, v218
	v_rcp_f32_e32 v219, v219
	v_pk_mul_f32 v[188:189], v[188:189], v[212:213]
	v_pk_mul_f32 v[190:191], v[190:191], v[214:215]
	v_pk_mul_f32 v[192:193], v[192:193], v[216:217]
	v_pk_mul_f32 v[194:195], v[194:195], v[218:219]
	v_cvt_pk_bf16_f32 v196, v188, v189
	v_cvt_pk_bf16_f32 v197, v190, v191
	v_cvt_pk_bf16_f32 v198, v192, v193
	v_cvt_pk_bf16_f32 v199, v194, v195
	ds_write_b128 v54, v[196:199] offset:6528
	v_add_u32_e32 v184, 56, v55
	v_add_u32_e32 v185, -1, v184
	v_mov_b32_e32 v166, 0
	v_mov_b32_e32 v167, 0
	v_mov_b32_e32 v168, 0
	v_mov_b32_e32 v169, 0
	v_mov_b32_e32 v170, 0
	v_mov_b32_e32 v171, 0
	v_mov_b32_e32 v172, 0
	v_mov_b32_e32 v173, 0
	v_mov_b32_e32 v174, 0
	v_mov_b32_e32 v175, 0
	v_mov_b32_e32 v176, 0
	v_mov_b32_e32 v177, 0
	v_mad_i64_i32 v[186:187], s[0:1], v185, s2, v[18:19]
	v_cmp_lt_u32_e64 s[0:1], 2, v184
	s_and_saveexec_b64 s[4:5], s[0:1]
	global_load_dwordx4 v[166:169], v[186:187], off offset:-4096
	s_or_b64 exec, exec, s[4:5]
	v_cmp_lt_u32_e64 s[0:1], 1, v184
	s_and_saveexec_b64 s[4:5], s[0:1]
	global_load_dwordx4 v[170:173], v[186:187], off offset:-2048
	s_or_b64 exec, exec, s[4:5]
	v_cmp_ne_u32_e64 s[0:1], 0, v184
	s_and_saveexec_b64 s[4:5], s[0:1]
	global_load_dwordx4 v[174:177], v[186:187], off
	s_or_b64 exec, exec, s[4:5]
	global_load_dwordx4 v[178:181], v[186:187], off offset:2048
	s_waitcnt vmcnt(12)
; DI unsigned pack2(float a, float b) { const f32x2 v = {a, b}; return __builtin_bit_cast(unsigned, __builtin_convertvector(v, bf16v2)); }
; DI void conv_unit(const u16* __restrict__ PM, const float* __restrict__ conv_w, const float* __restrict__ conv_b, int b, int sl0, int ch, float scale, float* a8) {
;   { const float4 b0 = *(const float4*)(conv_b + ch), b1 = *(const float4*)(conv_b + ch + 4); a8[0] = b0.x; a8[1] = b0.y; a8[2] = b0.z; a8[3] = b0.w; a8[4] = b1.x; a8[5] = b1.y; a8[6] = b1.z; a8[7] = b1.w; }
; #pragma unroll
;   for (int j = 0; j < 4; ++j) {
;     const int sl = sl0 - 3 + j;
;     if (sl >= 0) {
;       const uint4 raw = *(const uint4*)(PM + ((size_t)b * SEQ + sl) * 1024 + ch);
;       float x8[8]; unpack8(raw, x8);
;       const float4 w0 = *(const float4*)(conv_w + j * 1024 + ch), w1 = *(const float4*)(conv_w + j * 1024 + ch + 4);
;       a8[0] += w0.x * x8[0]; a8[1] += w0.y * x8[1]; a8[2] += w0.z * x8[2]; a8[3] += w0.w * x8[3];
;       a8[4] += w1.x * x8[4]; a8[5] += w1.y * x8[5]; a8[6] += w1.z * x8[6]; a8[7] += w1.w * x8[7];
;     }
;   }
; #pragma unroll
;   for (int e = 0; e < 8; ++e) { const float v = a8[e]; a8[e] = scale * v * __builtin_amdgcn_rcpf(1.f + __expf(-v)); }
; }
; DI void mlstmC_pair(const Params& p, char* lds_all, int pair) {
;     ...
;   for (int i = 0; i < 8; ++i) {
;     const int cg8 = ltid & 31, isK = cg8 >> 4, chl = (cg8 & 15) * 8, t = (ltid >> 5) + 8 * i;
;     float a8[8];
;     conv_unit(PM, p.in[5], p.in[6], b, c * 64 + t, (isK ? 512 : 0) + hd * 128 + chl, isK ? 0.08838834764831845f : 1.f, a8);
;     uint4 o; o.x = pack2(a8[0], a8[1]); o.y = pack2(a8[2], a8[3]); o.z = pack2(a8[4], a8[5]); o.w = pack2(a8[6], a8[7]);
;     *(uint4*)((isK ? Ks : Qs) + t * 136 + chl) = o;
	v_lshlrev_b32_e32 v188, 16, v118
	v_and_b32_e32 v189, 0xffff0000, v118
	v_lshlrev_b32_e32 v190, 16, v119
	v_and_b32_e32 v191, 0xffff0000, v119
	v_lshlrev_b32_e32 v192, 16, v120
	v_and_b32_e32 v193, 0xffff0000, v120
	v_lshlrev_b32_e32 v194, 16, v121
	v_and_b32_e32 v195, 0xffff0000, v121
	v_pk_fma_f32 v[204:205], v[94:95], v[188:189], v[4:5]
	v_pk_fma_f32 v[206:207], v[96:97], v[190:191], v[6:7]
	v_pk_fma_f32 v[208:209], v[98:99], v[192:193], v[0:1]
	v_pk_fma_f32 v[210:211], v[100:101], v[194:195], v[2:3]
	v_lshlrev_b32_e32 v188, 16, v122
	v_and_b32_e32 v189, 0xffff0000, v122
	v_lshlrev_b32_e32 v190, 16, v123
	v_and_b32_e32 v191, 0xffff0000, v123
	v_lshlrev_b32_e32 v192, 16, v124
	v_and_b32_e32 v193, 0xffff0000, v124
	v_lshlrev_b32_e32 v194, 16, v125
	v_and_b32_e32 v195, 0xffff0000, v125
	v_pk_fma_f32 v[204:205], v[102:103], v[188:189], v[204:205]
	v_pk_fma_f32 v[206:207], v[104:105], v[190:191], v[206:207]
	v_pk_fma_f32 v[208:209], v[106:107], v[192:193], v[208:209]
	v_pk_fma_f32 v[210:211], v[108:109], v[194:195], v[210:211]
	v_lshlrev_b32_e32 v188, 16, v126
	v_and_b32_e32 v189, 0xffff0000, v126
	v_lshlrev_b32_e32 v190, 16, v127
	v_and_b32_e32 v191, 0xffff0000, v127
	v_lshlrev_b32_e32 v192, 16, v128
	v_and_b32_e32 v193, 0xffff0000, v128
	v_lshlrev_b32_e32 v194, 16, v129
	v_and_b32_e32 v195, 0xffff0000, v129
	v_pk_fma_f32 v[204:205], v[110:111], v[188:189], v[204:205]
	v_pk_fma_f32 v[206:207], v[112:113], v[190:191], v[206:207]
	v_pk_fma_f32 v[208:209], v[114:115], v[192:193], v[208:209]
	v_pk_fma_f32 v[210:211], v[116:117], v[194:195], v[210:211]
	v_lshlrev_b32_e32 v188, 16, v130
	v_and_b32_e32 v189, 0xffff0000, v130
	v_lshlrev_b32_e32 v190, 16, v131
	v_and_b32_e32 v191, 0xffff0000, v131
	v_lshlrev_b32_e32 v192, 16, v132
	v_and_b32_e32 v193, 0xffff0000, v132
	v_lshlrev_b32_e32 v194, 16, v133
	v_and_b32_e32 v195, 0xffff0000, v133
	v_pk_fma_f32 v[204:205], v[8:9], v[188:189], v[204:205]
	v_pk_fma_f32 v[206:207], v[10:11], v[190:191], v[206:207]
	v_pk_fma_f32 v[208:209], v[12:13], v[192:193], v[208:209]
	v_pk_fma_f32 v[210:211], v[14:15], v[194:195], v[210:211]
	v_mul_f32_e32 v212, 0xbfb8aa3b, v204
	v_mul_f32_e32 v213, 0xbfb8aa3b, v205
	v_mul_f32_e32 v214, 0xbfb8aa3b, v206
	v_mul_f32_e32 v215, 0xbfb8aa3b, v207
	v_mul_f32_e32 v216, 0xbfb8aa3b, v208
	v_mul_f32_e32 v217, 0xbfb8aa3b, v209
	v_mul_f32_e32 v218, 0xbfb8aa3b, v210
	v_mul_f32_e32 v219, 0xbfb8aa3b, v211
	v_pk_mul_f32 v[188:189], v[26:27], v[204:205]
	v_pk_mul_f32 v[190:191], v[26:27], v[206:207]
	v_pk_mul_f32 v[192:193], v[26:27], v[208:209]
	v_pk_mul_f32 v[194:195], v[26:27], v[210:211]
	v_exp_f32_e32 v212, v212
	v_exp_f32_e32 v213, v213
	v_exp_f32_e32 v214, v214
	v_exp_f32_e32 v215, v215
	v_exp_f32_e32 v216, v216
	v_exp_f32_e32 v217, v217
	v_exp_f32_e32 v218, v218
	v_exp_f32_e32 v219, v219
	v_add_f32_e32 v212, 1.0, v212
	v_add_f32_e32 v213, 1.0, v213
	v_add_f32_e32 v214, 1.0, v214
	v_add_f32_e32 v215, 1.0, v215
	v_add_f32_e32 v216, 1.0, v216
	v_add_f32_e32 v217, 1.0, v217
	v_add_f32_e32 v218, 1.0, v218
	v_add_f32_e32 v219, 1.0, v219
	v_rcp_f32_e32 v212, v212
	v_rcp_f32_e32 v213, v213
	v_rcp_f32_e32 v214, v214
	v_rcp_f32_e32 v215, v215
	v_rcp_f32_e32 v216, v216
	v_rcp_f32_e32 v217, v217
	v_rcp_f32_e32 v218, v218
	v_rcp_f32_e32 v219, v219
	v_pk_mul_f32 v[188:189], v[188:189], v[212:213]
	v_pk_mul_f32 v[190:191], v[190:191], v[214:215]
	v_pk_mul_f32 v[192:193], v[192:193], v[216:217]
	v_pk_mul_f32 v[194:195], v[194:195], v[218:219]
	v_cvt_pk_bf16_f32 v196, v188, v189
	v_cvt_pk_bf16_f32 v197, v190, v191
	v_cvt_pk_bf16_f32 v198, v192, v193
	v_cvt_pk_bf16_f32 v199, v194, v195
	ds_write_b128 v54, v[196:199] offset:8704
	s_waitcnt vmcnt(8)
	v_lshlrev_b32_e32 v188, 16, v134
	v_and_b32_e32 v189, 0xffff0000, v134
	v_lshlrev_b32_e32 v190, 16, v135
	v_and_b32_e32 v191, 0xffff0000, v135
	v_lshlrev_b32_e32 v192, 16, v136
	v_and_b32_e32 v193, 0xffff0000, v136
	v_lshlrev_b32_e32 v194, 16, v137
	v_and_b32_e32 v195, 0xffff0000, v137
	v_pk_fma_f32 v[204:205], v[94:95], v[188:189], v[4:5]
	v_pk_fma_f32 v[206:207], v[96:97], v[190:191], v[6:7]
	v_pk_fma_f32 v[208:209], v[98:99], v[192:193], v[0:1]
	v_pk_fma_f32 v[210:211], v[100:101], v[194:195], v[2:3]
	v_lshlrev_b32_e32 v188, 16, v138
	v_and_b32_e32 v189, 0xffff0000, v138
	v_lshlrev_b32_e32 v190, 16, v139
	v_and_b32_e32 v191, 0xffff0000, v139
	v_lshlrev_b32_e32 v192, 16, v140
	v_and_b32_e32 v193, 0xffff0000, v140
	v_lshlrev_b32_e32 v194, 16, v141
	v_and_b32_e32 v195, 0xffff0000, v141
	v_pk_fma_f32 v[204:205], v[102:103], v[188:189], v[204:205]
	v_pk_fma_f32 v[206:207], v[104:105], v[190:191], v[206:207]
	v_pk_fma_f32 v[208:209], v[106:107], v[192:193], v[208:209]
	v_pk_fma_f32 v[210:211], v[108:109], v[194:195], v[210:211]
	v_lshlrev_b32_e32 v188, 16, v142
	v_and_b32_e32 v189, 0xffff0000, v142
	v_lshlrev_b32_e32 v190, 16, v143
	v_and_b32_e32 v191, 0xffff0000, v143
	v_lshlrev_b32_e32 v192, 16, v144
	v_and_b32_e32 v193, 0xffff0000, v144
	v_lshlrev_b32_e32 v194, 16, v145
	v_and_b32_e32 v195, 0xffff0000, v145
	v_pk_fma_f32 v[204:205], v[110:111], v[188:189], v[204:205]
	v_pk_fma_f32 v[206:207], v[112:113], v[190:191], v[206:207]
	v_pk_fma_f32 v[208:209], v[114:115], v[192:193], v[208:209]
	v_pk_fma_f32 v[210:211], v[116:117], v[194:195], v[210:211]
	v_lshlrev_b32_e32 v188, 16, v146
	v_and_b32_e32 v189, 0xffff0000, v146
	v_lshlrev_b32_e32 v190, 16, v147
	v_and_b32_e32 v191, 0xffff0000, v147
	v_lshlrev_b32_e32 v192, 16, v148
	v_and_b32_e32 v193, 0xffff0000, v148
	v_lshlrev_b32_e32 v194, 16, v149
	v_and_b32_e32 v195, 0xffff0000, v149
	v_pk_fma_f32 v[204:205], v[8:9], v[188:189], v[204:205]
	v_pk_fma_f32 v[206:207], v[10:11], v[190:191], v[206:207]
; DI unsigned pack2(float a, float b) { const f32x2 v = {a, b}; return __builtin_bit_cast(unsigned, __builtin_convertvector(v, bf16v2)); }
; DI void conv_unit(const u16* __restrict__ PM, const float* __restrict__ conv_w, const float* __restrict__ conv_b, int b, int sl0, int ch, float scale, float* a8) {
;   { const float4 b0 = *(const float4*)(conv_b + ch), b1 = *(const float4*)(conv_b + ch + 4); a8[0] = b0.x; a8[1] = b0.y; a8[2] = b0.z; a8[3] = b0.w; a8[4] = b1.x; a8[5] = b1.y; a8[6] = b1.z; a8[7] = b1.w; }
; #pragma unroll
;   for (int j = 0; j < 4; ++j) {
;     const int sl = sl0 - 3 + j;
;     if (sl >= 0) {
;       const uint4 raw = *(const uint4*)(PM + ((size_t)b * SEQ + sl) * 1024 + ch);
;       float x8[8]; unpack8(raw, x8);
;       const float4 w0 = *(const float4*)(conv_w + j * 1024 + ch), w1 = *(const float4*)(conv_w + j * 1024 + ch + 4);
;       a8[0] += w0.x * x8[0]; a8[1] += w0.y * x8[1]; a8[2] += w0.z * x8[2]; a8[3] += w0.w * x8[3];
;       a8[4] += w1.x * x8[4]; a8[5] += w1.y * x8[5]; a8[6] += w1.z * x8[6]; a8[7] += w1.w * x8[7];
;     }
;   }
; #pragma unroll
;   for (int e = 0; e < 8; ++e) { const float v = a8[e]; a8[e] = scale * v * __builtin_amdgcn_rcpf(1.f + __expf(-v)); }
; }
; DI void mlstmC_pair(const Params& p, char* lds_all, int pair) {
;     ...
;   for (int i = 0; i < 8; ++i) {
;     const int cg8 = ltid & 31, isK = cg8 >> 4, chl = (cg8 & 15) * 8, t = (ltid >> 5) + 8 * i;
;     float a8[8];
;     conv_unit(PM, p.in[5], p.in[6], b, c * 64 + t, (isK ? 512 : 0) + hd * 128 + chl, isK ? 0.08838834764831845f : 1.f, a8);
;     uint4 o; o.x = pack2(a8[0], a8[1]); o.y = pack2(a8[2], a8[3]); o.z = pack2(a8[4], a8[5]); o.w = pack2(a8[6], a8[7]);
;     *(uint4*)((isK ? Ks : Qs) + t * 136 + chl) = o;
	v_pk_fma_f32 v[208:209], v[12:13], v[192:193], v[208:209]
	v_pk_fma_f32 v[210:211], v[14:15], v[194:195], v[210:211]
	v_mul_f32_e32 v212, 0xbfb8aa3b, v204
	v_mul_f32_e32 v213, 0xbfb8aa3b, v205
	v_mul_f32_e32 v214, 0xbfb8aa3b, v206
	v_mul_f32_e32 v215, 0xbfb8aa3b, v207
	v_mul_f32_e32 v216, 0xbfb8aa3b, v208
	v_mul_f32_e32 v217, 0xbfb8aa3b, v209
	v_mul_f32_e32 v218, 0xbfb8aa3b, v210
	v_mul_f32_e32 v219, 0xbfb8aa3b, v211
	v_pk_mul_f32 v[188:189], v[26:27], v[204:205]
	v_pk_mul_f32 v[190:191], v[26:27], v[206:207]
	v_pk_mul_f32 v[192:193], v[26:27], v[208:209]
	v_pk_mul_f32 v[194:195], v[26:27], v[210:211]
	v_exp_f32_e32 v212, v212
	v_exp_f32_e32 v213, v213
	v_exp_f32_e32 v214, v214
	v_exp_f32_e32 v215, v215
	v_exp_f32_e32 v216, v216
	v_exp_f32_e32 v217, v217
	v_exp_f32_e32 v218, v218
	v_exp_f32_e32 v219, v219
	v_add_f32_e32 v212, 1.0, v212
	v_add_f32_e32 v213, 1.0, v213
	v_add_f32_e32 v214, 1.0, v214
	v_add_f32_e32 v215, 1.0, v215
	v_add_f32_e32 v216, 1.0, v216
	v_add_f32_e32 v217, 1.0, v217
	v_add_f32_e32 v218, 1.0, v218
	v_add_f32_e32 v219, 1.0, v219
	v_rcp_f32_e32 v212, v212
	v_rcp_f32_e32 v213, v213
	v_rcp_f32_e32 v214, v214
	v_rcp_f32_e32 v215, v215
	v_rcp_f32_e32 v216, v216
	v_rcp_f32_e32 v217, v217
	v_rcp_f32_e32 v218, v218
	v_rcp_f32_e32 v219, v219
	v_pk_mul_f32 v[188:189], v[188:189], v[212:213]
	v_pk_mul_f32 v[190:191], v[190:191], v[214:215]
	v_pk_mul_f32 v[192:193], v[192:193], v[216:217]
	v_pk_mul_f32 v[194:195], v[194:195], v[218:219]
	v_cvt_pk_bf16_f32 v196, v188, v189
	v_cvt_pk_bf16_f32 v197, v190, v191
	v_cvt_pk_bf16_f32 v198, v192, v193
	v_cvt_pk_bf16_f32 v199, v194, v195
	ds_write_b128 v54, v[196:199] offset:10880
	s_waitcnt vmcnt(4)
	v_lshlrev_b32_e32 v188, 16, v150
	v_and_b32_e32 v189, 0xffff0000, v150
	v_lshlrev_b32_e32 v190, 16, v151
	v_and_b32_e32 v191, 0xffff0000, v151
	v_lshlrev_b32_e32 v192, 16, v152
	v_and_b32_e32 v193, 0xffff0000, v152
	v_lshlrev_b32_e32 v194, 16, v153
	v_and_b32_e32 v195, 0xffff0000, v153
	v_pk_fma_f32 v[204:205], v[94:95], v[188:189], v[4:5]
	v_pk_fma_f32 v[206:207], v[96:97], v[190:191], v[6:7]
	v_pk_fma_f32 v[208:209], v[98:99], v[192:193], v[0:1]
	v_pk_fma_f32 v[210:211], v[100:101], v[194:195], v[2:3]
	v_lshlrev_b32_e32 v188, 16, v154
	v_and_b32_e32 v189, 0xffff0000, v154
	v_lshlrev_b32_e32 v190, 16, v155
	v_and_b32_e32 v191, 0xffff0000, v155
	v_lshlrev_b32_e32 v192, 16, v156
	v_and_b32_e32 v193, 0xffff0000, v156
	v_lshlrev_b32_e32 v194, 16, v157
	v_and_b32_e32 v195, 0xffff0000, v157
	v_pk_fma_f32 v[204:205], v[102:103], v[188:189], v[204:205]
	v_pk_fma_f32 v[206:207], v[104:105], v[190:191], v[206:207]
	v_pk_fma_f32 v[208:209], v[106:107], v[192:193], v[208:209]
	v_pk_fma_f32 v[210:211], v[108:109], v[194:195], v[210:211]
	v_lshlrev_b32_e32 v188, 16, v158
	v_and_b32_e32 v189, 0xffff0000, v158
	v_lshlrev_b32_e32 v190, 16, v159
	v_and_b32_e32 v191, 0xffff0000, v159
	v_lshlrev_b32_e32 v192, 16, v160
	v_and_b32_e32 v193, 0xffff0000, v160
	v_lshlrev_b32_e32 v194, 16, v161
	v_and_b32_e32 v195, 0xffff0000, v161
	v_pk_fma_f32 v[204:205], v[110:111], v[188:189], v[204:205]
	v_pk_fma_f32 v[206:207], v[112:113], v[190:191], v[206:207]
	v_pk_fma_f32 v[208:209], v[114:115], v[192:193], v[208:209]
	v_pk_fma_f32 v[210:211], v[116:117], v[194:195], v[210:211]
	v_lshlrev_b32_e32 v188, 16, v162
	v_and_b32_e32 v189, 0xffff0000, v162
	v_lshlrev_b32_e32 v190, 16, v163
	v_and_b32_e32 v191, 0xffff0000, v163
	v_lshlrev_b32_e32 v192, 16, v164
	v_and_b32_e32 v193, 0xffff0000, v164
	v_lshlrev_b32_e32 v194, 16, v165
	v_and_b32_e32 v195, 0xffff0000, v165
	v_pk_fma_f32 v[204:205], v[8:9], v[188:189], v[204:205]
	v_pk_fma_f32 v[206:207], v[10:11], v[190:191], v[206:207]
	v_pk_fma_f32 v[208:209], v[12:13], v[192:193], v[208:209]
	v_pk_fma_f32 v[210:211], v[14:15], v[194:195], v[210:211]
	v_mul_f32_e32 v212, 0xbfb8aa3b, v204
	v_mul_f32_e32 v213, 0xbfb8aa3b, v205
	v_mul_f32_e32 v214, 0xbfb8aa3b, v206
	v_mul_f32_e32 v215, 0xbfb8aa3b, v207
	v_mul_f32_e32 v216, 0xbfb8aa3b, v208
	v_mul_f32_e32 v217, 0xbfb8aa3b, v209
	v_mul_f32_e32 v218, 0xbfb8aa3b, v210
	v_mul_f32_e32 v219, 0xbfb8aa3b, v211
	v_pk_mul_f32 v[188:189], v[26:27], v[204:205]
	v_pk_mul_f32 v[190:191], v[26:27], v[206:207]
	v_pk_mul_f32 v[192:193], v[26:27], v[208:209]
	v_pk_mul_f32 v[194:195], v[26:27], v[210:211]
	v_exp_f32_e32 v212, v212
	v_exp_f32_e32 v213, v213
	v_exp_f32_e32 v214, v214
	v_exp_f32_e32 v215, v215
	v_exp_f32_e32 v216, v216
	v_exp_f32_e32 v217, v217
	v_exp_f32_e32 v218, v218
	v_exp_f32_e32 v219, v219
	v_add_f32_e32 v212, 1.0, v212
	v_add_f32_e32 v213, 1.0, v213
	v_add_f32_e32 v214, 1.0, v214
	v_add_f32_e32 v215, 1.0, v215
	v_add_f32_e32 v216, 1.0, v216
	v_add_f32_e32 v217, 1.0, v217
	v_add_f32_e32 v218, 1.0, v218
	v_add_f32_e32 v219, 1.0, v219
	v_rcp_f32_e32 v212, v212
	v_rcp_f32_e32 v213, v213
	v_rcp_f32_e32 v214, v214
	v_rcp_f32_e32 v215, v215
	v_rcp_f32_e32 v216, v216
	v_rcp_f32_e32 v217, v217
	v_rcp_f32_e32 v218, v218
	v_rcp_f32_e32 v219, v219
	v_pk_mul_f32 v[188:189], v[188:189], v[212:213]
	v_pk_mul_f32 v[190:191], v[190:191], v[214:215]
	v_pk_mul_f32 v[192:193], v[192:193], v[216:217]
	v_pk_mul_f32 v[194:195], v[194:195], v[218:219]
	v_cvt_pk_bf16_f32 v196, v188, v189
	v_cvt_pk_bf16_f32 v197, v190, v191
	v_cvt_pk_bf16_f32 v198, v192, v193
	v_cvt_pk_bf16_f32 v199, v194, v195
	ds_write_b128 v54, v[196:199] offset:13056
	s_waitcnt vmcnt(0)
; DI float bf2f(u16 h) { return __uint_as_float(((unsigned)h) << 16); }
; DI float log_sigmoid(float f) { return fminf(f, 0.f) - log1pf(expf(-fabsf(f))); }
; DI float scan_sum(float v, int lane) { for (int o = 1; o < 64; o <<= 1) { float tv = __shfl_up(v, o); if (lane >= o) v += tv; } return v; }
; DI void conv_unit(const u16* __restrict__ PM, const float* __restrict__ conv_w, const float* __restrict__ conv_b, int b, int sl0, int ch, float scale, float* a8) {
;   { const float4 b0 = *(const float4*)(conv_b + ch), b1 = *(const float4*)(conv_b + ch + 4); a8[0] = b0.x; a8[1] = b0.y; a8[2] = b0.z; a8[3] = b0.w; a8[4] = b1.x; a8[5] = b1.y; a8[6] = b1.z; a8[7] = b1.w; }
; #pragma unroll
;   for (int j = 0; j < 4; ++j) {
;     const int sl = sl0 - 3 + j;
;     if (sl >= 0) {
;       const uint4 raw = *(const uint4*)(PM + ((size_t)b * SEQ + sl) * 1024 + ch);
;       float x8[8]; unpack8(raw, x8);
;       const float4 w0 = *(const float4*)(conv_w + j * 1024 + ch), w1 = *(const float4*)(conv_w + j * 1024 + ch + 4);
;       a8[0] += w0.x * x8[0]; a8[1] += w0.y * x8[1]; a8[2] += w0.z * x8[2]; a8[3] += w0.w * x8[3];
;       a8[4] += w1.x * x8[4]; a8[5] += w1.y * x8[5]; a8[6] += w1.z * x8[6]; a8[7] += w1.w * x8[7];
;     }
;   }
; #pragma unroll
;   for (int e = 0; e < 8; ++e) { const float v = a8[e]; a8[e] = scale * v * __builtin_amdgcn_rcpf(1.f + __expf(-v)); }
; }
; DI void mlstmC_pair(const Params& p, char* lds_all, int pair) {
;     ...
;   for (int i = 0; i < 4; ++i) {
;     const int q = ltid + 256 * i, e = q >> 3, s8 = (q & 7) * 8;
;     *(uint4*)(VTs + e * 72 + s8) = *(const uint4*)(VTm + ((size_t)(bh * 128 + e)) * SEQ + c * 64 + s8);
;   }
;   if (lwave == 0) {
;     const size_t row = (size_t)b * SEQ + c * 64 + lane;
;     const float ig = G[row * 8 + hd] + p.in[7][hd], fg = G[row * 8 + 4 + hd] + p.in[8][hd];
;     const float bc = scan_sum(log_sigmoid(fg), lane);
;     const float as = ig - bc;
;     const float gm = scan_max(as, lane);
;     const float mt = bc + fmaxf(mprev, gm);
;     a_s[lane] = as; c_t[lane] = bc - mt; wint[lane] = expf(bc + mprev - mt); emt[lane] = expf(-mt);
;   }
;   __syncthreads();
;   {
;     const int t = ltid & 63, part = ltid >> 6;
;     float acc = 0.f;
;     if (c > 0) for (int dd = 0; dd < 32; ++dd) acc += bf2f(Qs[t * 136 + part * 32 + dd]) * NP[part * 32 + dd];
	v_lshlrev_b32_e32 v188, 16, v166
	v_and_b32_e32 v189, 0xffff0000, v166
	v_lshlrev_b32_e32 v190, 16, v167
	v_and_b32_e32 v191, 0xffff0000, v167
	v_lshlrev_b32_e32 v192, 16, v168
	v_and_b32_e32 v193, 0xffff0000, v168
	v_lshlrev_b32_e32 v194, 16, v169
	v_and_b32_e32 v195, 0xffff0000, v169
	v_pk_fma_f32 v[204:205], v[94:95], v[188:189], v[4:5]
	v_pk_fma_f32 v[206:207], v[96:97], v[190:191], v[6:7]
	v_pk_fma_f32 v[208:209], v[98:99], v[192:193], v[0:1]
	v_pk_fma_f32 v[210:211], v[100:101], v[194:195], v[2:3]
	v_lshlrev_b32_e32 v188, 16, v170
	v_and_b32_e32 v189, 0xffff0000, v170
	v_lshlrev_b32_e32 v190, 16, v171
	v_and_b32_e32 v191, 0xffff0000, v171
	v_lshlrev_b32_e32 v192, 16, v172
	v_and_b32_e32 v193, 0xffff0000, v172
	v_lshlrev_b32_e32 v194, 16, v173
	v_and_b32_e32 v195, 0xffff0000, v173
	v_pk_fma_f32 v[204:205], v[102:103], v[188:189], v[204:205]
	v_pk_fma_f32 v[206:207], v[104:105], v[190:191], v[206:207]
	v_pk_fma_f32 v[208:209], v[106:107], v[192:193], v[208:209]
	v_pk_fma_f32 v[210:211], v[108:109], v[194:195], v[210:211]
	v_lshlrev_b32_e32 v188, 16, v174
	v_and_b32_e32 v189, 0xffff0000, v174
	v_lshlrev_b32_e32 v190, 16, v175
	v_and_b32_e32 v191, 0xffff0000, v175
	v_lshlrev_b32_e32 v192, 16, v176
	v_and_b32_e32 v193, 0xffff0000, v176
	v_lshlrev_b32_e32 v194, 16, v177
	v_and_b32_e32 v195, 0xffff0000, v177
	v_pk_fma_f32 v[204:205], v[110:111], v[188:189], v[204:205]
	v_pk_fma_f32 v[206:207], v[112:113], v[190:191], v[206:207]
	v_pk_fma_f32 v[208:209], v[114:115], v[192:193], v[208:209]
	v_pk_fma_f32 v[210:211], v[116:117], v[194:195], v[210:211]
	v_lshlrev_b32_e32 v188, 16, v178
	v_and_b32_e32 v189, 0xffff0000, v178
	v_lshlrev_b32_e32 v190, 16, v179
	v_and_b32_e32 v191, 0xffff0000, v179
	v_lshlrev_b32_e32 v192, 16, v180
	v_and_b32_e32 v193, 0xffff0000, v180
	v_lshlrev_b32_e32 v194, 16, v181
	v_and_b32_e32 v195, 0xffff0000, v181
	v_pk_fma_f32 v[204:205], v[8:9], v[188:189], v[204:205]
	v_pk_fma_f32 v[206:207], v[10:11], v[190:191], v[206:207]
	v_pk_fma_f32 v[208:209], v[12:13], v[192:193], v[208:209]
	v_pk_fma_f32 v[210:211], v[14:15], v[194:195], v[210:211]
	v_mul_f32_e32 v212, 0xbfb8aa3b, v204
	v_mul_f32_e32 v213, 0xbfb8aa3b, v205
	v_mul_f32_e32 v214, 0xbfb8aa3b, v206
	v_mul_f32_e32 v215, 0xbfb8aa3b, v207
	v_mul_f32_e32 v216, 0xbfb8aa3b, v208
	v_mul_f32_e32 v217, 0xbfb8aa3b, v209
	v_mul_f32_e32 v218, 0xbfb8aa3b, v210
	v_mul_f32_e32 v219, 0xbfb8aa3b, v211
	v_pk_mul_f32 v[188:189], v[26:27], v[204:205]
	v_pk_mul_f32 v[190:191], v[26:27], v[206:207]
	v_pk_mul_f32 v[192:193], v[26:27], v[208:209]
	v_pk_mul_f32 v[194:195], v[26:27], v[210:211]
	v_exp_f32_e32 v212, v212
	v_exp_f32_e32 v213, v213
	v_exp_f32_e32 v214, v214
	v_exp_f32_e32 v215, v215
	v_exp_f32_e32 v216, v216
	v_exp_f32_e32 v217, v217
	v_exp_f32_e32 v218, v218
	v_exp_f32_e32 v219, v219
	v_add_f32_e32 v212, 1.0, v212
	v_add_f32_e32 v213, 1.0, v213
	v_add_f32_e32 v214, 1.0, v214
	v_add_f32_e32 v215, 1.0, v215
	v_add_f32_e32 v216, 1.0, v216
	v_add_f32_e32 v217, 1.0, v217
	v_add_f32_e32 v218, 1.0, v218
	v_add_f32_e32 v219, 1.0, v219
	v_rcp_f32_e32 v212, v212
	v_rcp_f32_e32 v213, v213
	v_rcp_f32_e32 v214, v214
	v_rcp_f32_e32 v215, v215
	v_rcp_f32_e32 v216, v216
	v_rcp_f32_e32 v217, v217
	v_rcp_f32_e32 v218, v218
	v_rcp_f32_e32 v219, v219
	v_pk_mul_f32 v[188:189], v[188:189], v[212:213]
	v_pk_mul_f32 v[190:191], v[190:191], v[214:215]
	v_pk_mul_f32 v[192:193], v[192:193], v[216:217]
	v_pk_mul_f32 v[194:195], v[194:195], v[218:219]
	v_cvt_pk_bf16_f32 v196, v188, v189
	v_cvt_pk_bf16_f32 v197, v190, v191
	v_cvt_pk_bf16_f32 v198, v192, v193
	v_cvt_pk_bf16_f32 v199, v194, v195
	ds_write_b128 v54, v[196:199] offset:15232
.LBB0_580:
	v_lshlrev_b32_e32 v20, 7, v53
	v_lshlrev_b32_e32 v2, 1, v52
	v_lshl_add_u64 v[0:1], s[56:57], 0, v[20:21]
	v_and_b32_e32 v20, 0x70, v2
	v_lshrrev_b32_e32 v2, 3, v42
	s_movk_i32 s0, 0xff80
	v_and_or_b32 v6, v45, s0, v2
	v_ashrrev_i32_e32 v7, 31, v6
	v_lshl_add_u64 v[4:5], v[0:1], 0, v[20:21]
	v_lshlrev_b64 v[0:1], 14, v[6:7]
	v_lshl_add_u64 v[0:1], v[4:5], 0, v[0:1]
	v_mul_u32_u24_e32 v2, 0x90, v2
	v_add3_u32 v7, v51, v20, v2
	global_load_dwordx4 v[0:3], v[0:1], off
	v_lshlrev_b32_e32 v36, 6, v53
	v_and_b32_e32 v26, 63, v46
	v_cmp_gt_u32_e64 s[0:1], 64, v42
	v_lshlrev_b64 v[22:23], 13, v[16:17]
	v_mbcnt_hi_u32_b32 v27, -1, v203
	v_or_b32_e32 v184, 32, v6
	v_ashrrev_i32_e32 v185, 31, v184
	v_lshlrev_b64 v[184:185], 14, v[184:185]
	v_lshl_add_u64 v[184:185], v[4:5], 0, v[184:185]
	global_load_dwordx4 v[118:121], v[184:185], off
	v_or_b32_e32 v184, 64, v6
	v_ashrrev_i32_e32 v185, 31, v184
	v_lshlrev_b64 v[184:185], 14, v[184:185]
	v_lshl_add_u64 v[184:185], v[4:5], 0, v[184:185]
	global_load_dwordx4 v[122:125], v[184:185], off
	v_or_b32_e32 v184, 0x60, v6
	v_ashrrev_i32_e32 v185, 31, v184
	v_lshlrev_b64 v[184:185], 14, v[184:185]
	v_lshl_add_u64 v[184:185], v[4:5], 0, v[184:185]
	global_load_dwordx4 v[126:129], v[184:185], off
	v_lshlrev_b64 v[200:201], 9, v[24:25]
	v_lshl_add_u64 v[200:201], s[60:61], 0, v[200:201]
	v_lshrrev_b32_e32 v202, 6, v42
	v_lshlrev_b32_e32 v248, 7, v202
	v_mov_b32_e32 v249, 0
	v_lshl_add_u64 v[200:201], v[200:201], 0, v[248:249]
	global_load_dwordx4 v[94:97], v[200:201], off
	global_load_dwordx4 v[98:101], v[200:201], off offset:16
	global_load_dwordx4 v[102:105], v[200:201], off offset:32
	global_load_dwordx4 v[106:109], v[200:201], off offset:48
	global_load_dwordx4 v[110:113], v[200:201], off offset:64
	global_load_dwordx4 v[114:117], v[200:201], off offset:80
	global_load_dwordx4 v[212:215], v[200:201], off offset:96
	global_load_dwordx4 v[216:219], v[200:201], off offset:112
	v_lshlrev_b64 v[200:201], 15, v[24:25]
	v_lshl_add_u64 v[200:201], s[58:59], 0, v[200:201]
	v_and_b32_e32 v248, 31, v46
	v_lshlrev_b32_e32 v248, 8, v248
	v_lshl_or_b32 v248, v202, 13, v248
	v_and_b32_e32 v202, 32, v46
	v_lshrrev_b32_e32 v202, 1, v202
	v_or_b32_e32 v248, v248, v202
	v_lshl_add_u64 v[200:201], v[200:201], 0, v[248:249]
	global_load_dwordx4 v[130:133], v[200:201], off
	global_load_dwordx4 v[134:137], v[200:201], off offset:32
	global_load_dwordx4 v[138:141], v[200:201], off offset:64
	global_load_dwordx4 v[142:145], v[200:201], off offset:96
	global_load_dwordx4 v[146:149], v[200:201], off offset:128
	global_load_dwordx4 v[224:227], v[200:201], off offset:160
	global_load_dwordx4 v[228:231], v[200:201], off offset:192
	global_load_dwordx4 v[232:235], v[200:201], off offset:224
	s_waitcnt vmcnt(19)
	ds_write_b128 v7, v[0:3] offset:34816
	s_waitcnt vmcnt(18)
	ds_write_b128 v7, v[118:121] offset:39424
	s_waitcnt vmcnt(17)
	ds_write_b128 v7, v[122:125] offset:44032
	s_waitcnt vmcnt(16)
	ds_write_b128 v7, v[126:129] offset:48640
	s_and_saveexec_b64 s[6:7], s[0:1]
	s_cbranch_execz .LBB0_582
; DI float log_sigmoid(float f) { return fminf(f, 0.f) - log1pf(expf(-fabsf(f))); }
; DI float scan_sum(float v, int lane) { for (int o = 1; o < 64; o <<= 1) { float tv = __shfl_up(v, o); if (lane >= o) v += tv; } return v; }
; DI float scan_max(float v, int lane) { for (int o = 1; o < 64; o <<= 1) { float tv = __shfl_up(v, o); if (lane >= o) v = fmaxf(v, tv); } return v; }
; DI void mlstmC_pair(const Params& p, char* lds_all, int pair) {
;     ...
;   if (lwave == 0) {
;     const size_t row = (size_t)b * SEQ + c * 64 + lane;
;     const float ig = G[row * 8 + hd] + p.in[7][hd], fg = G[row * 8 + 4 + hd] + p.in[8][hd];
;     const float bc = scan_sum(log_sigmoid(fg), lane);
;     const float as = ig - bc;
;     const float gm = scan_max(as, lane);
;     const float mt = bc + fmaxf(mprev, gm);
;     a_s[lane] = as; c_t[lane] = bc - mt; wint[lane] = expf(bc + mprev - mt); emt[lane] = expf(-mt);
;   }
	v_lshlrev_b32_e32 v20, 2, v44
	v_add_f32_e32 v0, v182, v221
	s_mov_b32 s0, 0xb2a5705f
	v_add_f32_e32 v1, v220, v223
	v_mul_f32_e64 v2, |v1|, s19
	v_fma_f32 v3, |v1|, s19, -v2
	v_rndne_f32_e32 v5, v2
	v_fma_f32 v3, |v1|, s0, v3
	v_sub_f32_e32 v2, v2, v5
	v_add_f32_e32 v2, v2, v3
	v_exp_f32_e32 v2, v2
	v_cvt_i32_f32_e32 v3, v5
	v_cmp_ngt_f32_e64 s[0:1], |v1|, s20
	v_min_f32_e32 v4, 0, v1
	v_ldexp_f32 v2, v2, v3
	v_cndmask_b32_e64 v2, 0, v2, s[0:1]
	v_cmp_nlt_f32_e64 s[0:1], |v1|, s21
	s_nop 1
	v_cndmask_b32_e64 v1, v50, v2, s[0:1]
	v_add_f32_e32 v5, 1.0, v1
	v_add_f32_e32 v2, -1.0, v5
	v_sub_f32_e32 v3, v2, v5
	v_add_f32_e32 v3, 1.0, v3
	v_sub_f32_e32 v2, v1, v2
	v_add_f32_e32 v6, v2, v3
	v_frexp_mant_f32_e32 v2, v5
	s_mov_b32 s0, 0x3f2aaaab
	v_cmp_gt_f32_e64 s[0:1], s0, v2
	v_cvt_f64_f32_e32 v[2:3], v5
	v_frexp_exp_i32_f64_e32 v2, v[2:3]
	v_subbrev_co_u32_e64 v2, s[0:1], 0, v2, s[0:1]
	v_sub_u32_e32 v3, 0, v2
	v_ldexp_f32 v5, v5, v3
	v_ldexp_f32 v3, v6, v3
	v_add_f32_e32 v6, -1.0, v5
	v_add_f32_e32 v7, 1.0, v6
	v_sub_f32_e32 v7, v5, v7
	v_add_f32_e32 v7, v3, v7
	v_add_f32_e32 v8, v6, v7
	v_sub_f32_e32 v6, v6, v8
	v_add_f32_e32 v6, v7, v6
	v_add_f32_e32 v7, 1.0, v5
	v_add_f32_e32 v9, -1.0, v7
	v_sub_f32_e32 v5, v5, v9
	v_add_f32_e32 v3, v3, v5
	v_add_f32_e32 v5, v7, v3
	v_sub_f32_e32 v7, v7, v5
	v_add_f32_e32 v3, v3, v7
	v_rcp_f32_e32 v7, v5
	v_cvt_f32_i32_e32 v2, v2
	s_mov_b32 s0, 0x3f317218
	v_mul_f32_e32 v9, v8, v7
	v_mul_f32_e32 v10, v5, v9
	v_fma_f32 v11, v9, v5, -v10
	v_fmac_f32_e32 v11, v9, v3
	v_add_f32_e32 v12, v10, v11
	v_sub_f32_e32 v13, v8, v12
	v_sub_f32_e32 v8, v8, v13
	v_sub_f32_e32 v10, v12, v10
	v_sub_f32_e32 v8, v8, v12
	v_add_f32_e32 v6, v6, v8
	v_sub_f32_e32 v8, v10, v11
	v_add_f32_e32 v6, v8, v6
	v_add_f32_e32 v8, v13, v6
	v_mul_f32_e32 v10, v7, v8
	v_mul_f32_e32 v11, v5, v10
	v_fma_f32 v5, v10, v5, -v11
	v_fmac_f32_e32 v5, v10, v3
	v_sub_f32_e32 v3, v13, v8
	v_add_f32_e32 v3, v6, v3
	v_add_f32_e32 v6, v11, v5
	v_sub_f32_e32 v12, v8, v6
	v_sub_f32_e32 v8, v8, v12
	v_sub_f32_e32 v11, v6, v11
	v_sub_f32_e32 v6, v8, v6
	v_add_f32_e32 v3, v3, v6
	v_sub_f32_e32 v5, v11, v5
	v_add_f32_e32 v3, v5, v3
	v_add_f32_e32 v5, v9, v10
	v_add_f32_e32 v3, v12, v3
	v_sub_f32_e32 v6, v5, v9
	v_mul_f32_e32 v3, v7, v3
	v_sub_f32_e32 v6, v10, v6
	v_add_f32_e32 v3, v6, v3
	v_mul_f32_e32 v9, 0x3f317218, v2
	v_add_f32_e32 v6, v5, v3
	v_fma_f32 v10, v2, s0, -v9
	v_mul_f32_e32 v7, v6, v6
	v_fmac_f32_e32 v10, 0xb102e308, v2
	v_sub_f32_e32 v2, v6, v5
	v_fmamk_f32 v8, v7, 0x3e9b6dac, v49
	v_sub_f32_e32 v2, v3, v2
	v_add_f32_e32 v3, v9, v10
	v_fmaak_f32 v8, v7, v8, 0x3f2aaada
	v_sub_f32_e32 v5, v3, v9
	v_ldexp_f32 v9, v6, 1
	v_mul_f32_e32 v6, v6, v7
	v_mul_f32_e32 v6, v6, v8
	v_add_f32_e32 v7, v9, v6
	v_sub_f32_e32 v8, v7, v9
	v_ldexp_f32 v2, v2, 1
	v_sub_f32_e32 v6, v6, v8
	v_add_f32_e32 v2, v2, v6
	v_add_f32_e32 v6, v7, v2
	v_sub_f32_e32 v7, v6, v7
	v_sub_f32_e32 v2, v2, v7
	v_add_f32_e32 v7, v3, v6
	v_sub_f32_e32 v8, v7, v3
	v_sub_f32_e32 v9, v7, v8
	v_sub_f32_e32 v5, v10, v5
	v_sub_f32_e32 v3, v3, v9
	v_sub_f32_e32 v6, v6, v8
	v_add_f32_e32 v3, v6, v3
	v_add_f32_e32 v6, v5, v2
	v_sub_f32_e32 v8, v6, v5
	v_sub_f32_e32 v9, v6, v8
	v_sub_f32_e32 v5, v5, v9
	v_sub_f32_e32 v2, v2, v8
	v_add_f32_e32 v3, v6, v3
	v_add_f32_e32 v2, v2, v5
	v_add_f32_e32 v5, v7, v3
	v_sub_f32_e32 v6, v5, v7
	v_sub_f32_e32 v3, v3, v6
	v_add_f32_e32 v2, v2, v3
	s_mov_b32 s0, 0x7f800000
	v_add_f32_e32 v2, v5, v2
	v_cmp_neq_f32_e64 s[0:1], s0, v1
	s_nop 1
	v_cndmask_b32_e64 v2, v50, v2, s[0:1]
	s_mov_b32 s0, 0x33800000
	v_cmp_lt_f32_e64 s[0:1], |v1|, s0
	s_nop 1
	v_cndmask_b32_e64 v1, v2, v1, s[0:1]
	v_sub_f32_e32 v3, v4, v1
	s_nop 1
	v_add_f32_dpp v3, v3, v3 row_shr:1 row_mask:0xf bank_mask:0xf
	s_nop 1
	v_add_f32_dpp v3, v3, v3 row_shr:2 row_mask:0xf bank_mask:0xf
	s_nop 1
	v_add_f32_dpp v3, v3, v3 row_shr:4 row_mask:0xf bank_mask:0xf
	s_nop 1
	v_add_f32_dpp v3, v3, v3 row_shr:8 row_mask:0xf bank_mask:0xf
	s_nop 1
	v_add_f32_dpp v3, v3, v3 row_bcast:15 row_mask:0xa bank_mask:0xf
	s_nop 1
	v_add_f32_dpp v3, v3, v3 row_bcast:31 row_mask:0xc bank_mask:0xf
	v_sub_f32_e32 v0, v0, v3
	v_mov_b32_e32 v1, v0
	s_nop 1
	v_max_f32_dpp v1, v1, v1 row_shr:1 row_mask:0xf bank_mask:0xf
	s_nop 1
	v_max_f32_dpp v1, v1, v1 row_shr:2 row_mask:0xf bank_mask:0xf
	s_nop 1
	v_max_f32_dpp v1, v1, v1 row_shr:4 row_mask:0xf bank_mask:0xf
	s_nop 1
	v_max_f32_dpp v1, v1, v1 row_shr:8 row_mask:0xf bank_mask:0xf
	s_nop 1
	v_max_f32_dpp v1, v1, v1 row_bcast:15 row_mask:0xa bank_mask:0xf
	s_nop 1
	v_max_f32_dpp v1, v1, v1 row_bcast:31 row_mask:0xc bank_mask:0xf
	s_mov_b32 s0, 0x3fb8aa3b
	v_max_f32_e32 v1, v1, v1
	v_max_f32_e32 v2, v43, v43
	v_max_f32_e32 v1, v2, v1
	v_add_f32_e32 v1, v3, v1
	v_lshl_add_u32 v2, v26, 2, v51
	v_sub_f32_e32 v4, v3, v1
	ds_write2st64_b32 v2, v0, v4 offset0:244 offset1:245
	v_add_f32_e32 v0, v43, v3
	v_sub_f32_e32 v0, v0, v1
	v_mul_f32_e32 v3, 0x3fb8aa3b, v0
	v_fma_f32 v4, v0, s0, -v3
	v_rndne_f32_e32 v5, v3
	v_fmac_f32_e32 v4, 0x32a5705f, v0
	v_sub_f32_e32 v3, v3, v5
	v_add_f32_e32 v3, v3, v4
	v_exp_f32_e32 v3, v3
	v_cvt_i32_f32_e32 v4, v5
	s_mov_b32 s0, 0xc2ce8ed0
	v_cmp_ngt_f32_e64 s[0:1], s0, v0
	v_ldexp_f32 v3, v3, v4
	s_nop 0
	v_cndmask_b32_e64 v3, 0, v3, s[0:1]
	s_mov_b32 s0, 0x42b17218
	v_cmp_nlt_f32_e64 s[0:1], s0, v0
	s_nop 1
	v_cndmask_b32_e64 v0, v50, v3, s[0:1]
	v_mul_f32_e32 v3, 0xbfb8aa3b, v1
	v_fma_f32 v4, v1, s19, -v3
	v_rndne_f32_e32 v5, v3
	v_fmac_f32_e32 v4, 0xb2a5705f, v1
	v_sub_f32_e32 v3, v3, v5
	v_add_f32_e32 v3, v3, v4
	v_exp_f32_e32 v3, v3
	v_cvt_i32_f32_e32 v4, v5
	v_cmp_nlt_f32_e64 s[0:1], s20, v1
	v_ldexp_f32 v3, v3, v4
	s_nop 0
	v_cndmask_b32_e64 v3, 0, v3, s[0:1]
	v_cmp_ngt_f32_e64 s[0:1], s21, v1
	s_nop 1
	v_cndmask_b32_e64 v1, v50, v3, s[0:1]
	ds_write2st64_b32 v2, v0, v1 offset0:246 offset1:247
; DI float bf2f(u16 h) { return __uint_as_float(((unsigned)h) << 16); }
; DI void mlstmC_pair(const Params& p, char* lds_all, int pair) {
;     ...
;   {
;     const int t = ltid & 63, part = ltid >> 6;
;     float acc = 0.f;
;     if (c > 0) for (int dd = 0; dd < 32; ++dd) acc += bf2f(Qs[t * 136 + part * 32 + dd]) * NP[part * 32 + dd];
;     qnp[part * 64 + t] = acc;
;   }
.LBB0_582:
	s_or_b64 exec, exec, s[6:7]
	v_lshrrev_b32_e32 v28, 6, v42
	v_lshlrev_b32_e32 v37, 5, v28
	v_mov_b32_e32 v29, 0
	v_mov_b32_e32 v0, 0
	s_waitcnt lgkmcnt(0)
	s_barrier
	s_and_saveexec_b64 s[0:1], vcc
	s_cbranch_execz .LBB0_584
	v_lshlrev_b64 v[0:1], 9, v[24:25]
	v_lshl_add_u64 v[16:17], s[60:61], 0, v[0:1]
	v_mul_u32_u24_e32 v0, 0x110, v26
	v_lshlrev_b32_e32 v1, 1, v37
	v_lshlrev_b32_e32 v20, 2, v37
	v_add3_u32 v4, v51, v0, v1
	v_lshl_add_u64 v[34:35], v[16:17], 0, v[20:21]
	ds_read_b128 v[0:3], v4
	ds_read_b128 v[12:15], v4 offset:16
	ds_read_b128 v[8:11], v4 offset:32
	ds_read_b128 v[4:7], v4 offset:48
	s_waitcnt lgkmcnt(3)
	v_lshlrev_b32_e32 v43, 16, v0
	v_and_b32_e32 v0, 0xffff0000, v0
	s_waitcnt vmcnt(8)
	v_fma_f32 v20, v94, v43, 0
	v_fmac_f32_e32 v20, v95, v0
	v_lshlrev_b32_e32 v0, 16, v1
	v_fmac_f32_e32 v20, v96, v0
	v_and_b32_e32 v0, 0xffff0000, v1
	v_fmac_f32_e32 v20, v97, v0
	v_lshlrev_b32_e32 v0, 16, v2
	v_fmac_f32_e32 v20, v98, v0
	v_and_b32_e32 v0, 0xffff0000, v2
	v_fmac_f32_e32 v20, v99, v0
	v_lshlrev_b32_e32 v0, 16, v3
	v_fmac_f32_e32 v20, v100, v0
	v_and_b32_e32 v0, 0xffff0000, v3
	v_fmac_f32_e32 v20, v101, v0
	s_waitcnt lgkmcnt(2)
	v_lshlrev_b32_e32 v0, 16, v12
	v_fmac_f32_e32 v20, v102, v0
	v_and_b32_e32 v0, 0xffff0000, v12
	v_fmac_f32_e32 v20, v103, v0
	v_lshlrev_b32_e32 v0, 16, v13
	v_fmac_f32_e32 v20, v104, v0
	v_and_b32_e32 v0, 0xffff0000, v13
	v_fmac_f32_e32 v20, v105, v0
	v_lshlrev_b32_e32 v0, 16, v14
	v_fmac_f32_e32 v20, v106, v0
	v_and_b32_e32 v0, 0xffff0000, v14
	v_fmac_f32_e32 v20, v107, v0
	v_lshlrev_b32_e32 v0, 16, v15
	v_fmac_f32_e32 v20, v108, v0
	v_and_b32_e32 v0, 0xffff0000, v15
	v_fmac_f32_e32 v20, v109, v0
	s_waitcnt lgkmcnt(1)
	v_lshlrev_b32_e32 v38, 16, v8
	v_and_b32_e32 v8, 0xffff0000, v8
	v_fmac_f32_e32 v20, v110, v38
	v_fmac_f32_e32 v20, v111, v8
	v_lshlrev_b32_e32 v8, 16, v9
	v_fmac_f32_e32 v20, v112, v8
	v_and_b32_e32 v8, 0xffff0000, v9
	v_fmac_f32_e32 v20, v113, v8
	v_and_b32_e32 v9, 0xffff0000, v10
	v_lshlrev_b32_e32 v8, 16, v10
	v_pk_mul_f32 v[8:9], v[114:115], v[8:9]
	s_nop 0
	v_add_f32_e32 v8, v20, v8
	v_add_f32_e32 v10, v8, v9
	v_and_b32_e32 v9, 0xffff0000, v11
	v_lshlrev_b32_e32 v8, 16, v11
	v_pk_mul_f32 v[8:9], v[116:117], v[8:9]
	s_nop 0
	v_add_f32_e32 v8, v10, v8
	v_add_f32_e32 v10, v8, v9
	s_waitcnt lgkmcnt(0)
	v_and_b32_e32 v9, 0xffff0000, v4
	v_lshlrev_b32_e32 v8, 16, v4
	v_pk_mul_f32 v[8:9], v[212:213], v[8:9]
	s_nop 0
	v_add_f32_e32 v4, v10, v8
	v_add_f32_e32 v10, v4, v9
	v_and_b32_e32 v9, 0xffff0000, v5
	v_lshlrev_b32_e32 v8, 16, v5
	v_pk_mul_f32 v[4:5], v[214:215], v[8:9]
	s_nop 0
	v_add_f32_e32 v4, v10, v4
	v_add_f32_e32 v8, v4, v5
	v_and_b32_e32 v5, 0xffff0000, v6
	v_lshlrev_b32_e32 v4, 16, v6
	v_pk_mul_f32 v[0:1], v[216:217], v[4:5]
	s_nop 0
	v_add_f32_e32 v0, v8, v0
	v_add_f32_e32 v4, v0, v1
	v_and_b32_e32 v1, 0xffff0000, v7
	v_lshlrev_b32_e32 v0, 16, v7
	v_pk_mul_f32 v[0:1], v[218:219], v[0:1]
	s_nop 0
	v_add_f32_e32 v0, v4, v0
	v_add_f32_e32 v0, v0, v1

; #define MFMA(a, b, c) __builtin_amdgcn_mfma_f32_32x32x16_bf16((a), (b), (c), 0, 0, 0)
; DI f32x16 zero16() { f32x16 z; for (int i = 0; i < 16; ++i) z[i] = 0.f; return z; }
; DI void mlstmC_pair(const Params& p, char* lds_all, int pair) {
;     ...
;   for (int tt = 0; tt < 2; ++tt) {
;     const int tq = tt * 32 + l31;
;     Hn[tt] = zero16();
;     if (c > 0) {
; #pragma unroll
;       for (int kk = 0; kk < 8; ++kk) Hn[tt] = MFMA(ldfrag(CT + (et * 32 + l31) * 128 + kk * 16 + 8 * hh), ldfrag(Qs + tq * 136 + kk * 16 + 8 * hh), Hn[tt]);
;     }
.LBB0_618:
	s_or_b64 exec, exec, s[4:5]
	s_waitcnt lgkmcnt(1)
	v_lshlrev_b64 v[2:3], 15, v[24:25]
	v_lshlrev_b32_e32 v0, 8, v53
	v_lshl_add_u64 v[2:3], s[58:59], 0, v[2:3]
	v_lshl_or_b32 v20, v28, 13, v0
	v_lshlrev_b32_e32 v18, 1, v1
	v_lshl_add_u64 v[0:1], v[2:3], 0, v[20:21]
	v_mov_b32_e32 v19, v21
	v_add_u32_e32 v29, v51, v18
	v_lshl_add_u64 v[16:17], v[0:1], 0, v[18:19]
	v_mov_b32_e32 v0, 0
	v_mov_b32_e32 v1, 0
	v_mov_b32_e32 v2, 0
	v_mov_b32_e32 v3, 0
	v_mov_b32_e32 v4, 0
	v_mov_b32_e32 v5, 0
	v_mov_b32_e32 v6, 0
	v_mov_b32_e32 v7, 0
	v_mov_b32_e32 v8, 0
	v_mov_b32_e32 v9, 0
	v_mov_b32_e32 v10, 0
	v_mov_b32_e32 v11, 0
	v_mov_b32_e32 v12, 0
	v_mov_b32_e32 v13, 0
	v_mov_b32_e32 v14, 0
	v_mov_b32_e32 v15, 0
	s_waitcnt lgkmcnt(0)
	s_barrier
	s_and_saveexec_b64 s[4:5], vcc
	s_cbranch_execz .LBB0_620
	v_mad_u32_u24 v19, v53, s18, v29
	ds_read_b128 v[150:153], v19
	ds_read_b128 v[154:157], v19 offset:32
	ds_read_b128 v[158:161], v19 offset:64
	ds_read_b128 v[162:165], v19 offset:96
	ds_read_b128 v[166:169], v19 offset:128
	ds_read_b128 v[170:173], v19 offset:160
	ds_read_b128 v[174:177], v19 offset:192
	ds_read_b128 v[178:181], v19 offset:224
	s_waitcnt vmcnt(0) lgkmcnt(7)
	v_mfma_f32_32x32x16_bf16 v[0:15], v[130:133], v[150:153], 0
	s_waitcnt lgkmcnt(6)
	v_mfma_f32_32x32x16_bf16 v[0:15], v[134:137], v[154:157], v[0:15]
	s_waitcnt lgkmcnt(5)
	v_mfma_f32_32x32x16_bf16 v[0:15], v[138:141], v[158:161], v[0:15]
	s_waitcnt lgkmcnt(4)
	v_mfma_f32_32x32x16_bf16 v[0:15], v[142:145], v[162:165], v[0:15]
	s_waitcnt lgkmcnt(3)
	v_mfma_f32_32x32x16_bf16 v[0:15], v[146:149], v[166:169], v[0:15]
	s_waitcnt lgkmcnt(2)
	v_mfma_f32_32x32x16_bf16 v[0:15], v[224:227], v[170:173], v[0:15]
	s_waitcnt lgkmcnt(1)
	v_mfma_f32_32x32x16_bf16 v[0:15], v[228:231], v[174:177], v[0:15]
	s_waitcnt lgkmcnt(0)
	v_mfma_f32_32x32x16_bf16 v[0:15], v[232:235], v[178:181], v[0:15]

; #define MFMA(a, b, c) __builtin_amdgcn_mfma_f32_32x32x16_bf16((a), (b), (c), 0, 0, 0)
; DI f32x16 zero16() { f32x16 z; for (int i = 0; i < 16; ++i) z[i] = 0.f; return z; }
; DI void mlstmC_pair(const Params& p, char* lds_all, int pair) {
;     ...
;   for (int tt = 0; tt < 2; ++tt) {
;     const int tq = tt * 32 + l31;
;     Hn[tt] = zero16();
;     if (c > 0) {
; #pragma unroll
;       for (int kk = 0; kk < 8; ++kk) Hn[tt] = MFMA(ldfrag(CT + (et * 32 + l31) * 128 + kk * 16 + 8 * hh), ldfrag(Qs + tq * 136 + kk * 16 + 8 * hh), Hn[tt]);
;     }
.LBB0_622:
	s_or_b64 exec, exec, s[4:5]
	v_or_b32_e32 v52, 32, v53
	v_mov_b32_e32 v0, 0
	v_mov_b32_e32 v1, 0
	s_waitcnt lgkmcnt(1)
	v_mov_b32_e32 v2, 0
	s_waitcnt lgkmcnt(0)
	v_mov_b32_e32 v3, 0
	v_mov_b32_e32 v4, 0
	v_mov_b32_e32 v5, 0
	v_mov_b32_e32 v6, 0
	v_mov_b32_e32 v7, 0
	v_mov_b32_e32 v8, 0
	v_mov_b32_e32 v9, 0
	v_mov_b32_e32 v10, 0
	v_mov_b32_e32 v11, 0
	v_mov_b32_e32 v12, 0
	v_mov_b32_e32 v13, 0
	v_mov_b32_e32 v14, 0
	v_mov_b32_e32 v15, 0
	s_and_saveexec_b64 s[4:5], vcc
	s_cbranch_execz .LBB0_624
	v_mad_u32_u24 v20, v52, s18, v29
	ds_read_b128 v[150:153], v20
	ds_read_b128 v[154:157], v20 offset:32
	ds_read_b128 v[158:161], v20 offset:64
	ds_read_b128 v[162:165], v20 offset:96
	ds_read_b128 v[166:169], v20 offset:128
	ds_read_b128 v[170:173], v20 offset:160
	ds_read_b128 v[174:177], v20 offset:192
	ds_read_b128 v[178:181], v20 offset:224
	s_waitcnt lgkmcnt(7)
	v_mfma_f32_32x32x16_bf16 v[0:15], v[130:133], v[150:153], 0
	s_waitcnt lgkmcnt(6)
	v_mfma_f32_32x32x16_bf16 v[0:15], v[134:137], v[154:157], v[0:15]
	s_waitcnt lgkmcnt(5)
	v_mfma_f32_32x32x16_bf16 v[0:15], v[138:141], v[158:161], v[0:15]
	s_waitcnt lgkmcnt(4)
	v_mfma_f32_32x32x16_bf16 v[0:15], v[142:145], v[162:165], v[0:15]
	s_waitcnt lgkmcnt(3)
	v_mfma_f32_32x32x16_bf16 v[0:15], v[146:149], v[166:169], v[0:15]
	s_waitcnt lgkmcnt(2)
	v_mfma_f32_32x32x16_bf16 v[0:15], v[224:227], v[170:173], v[0:15]
	s_waitcnt lgkmcnt(1)
	v_mfma_f32_32x32x16_bf16 v[0:15], v[228:231], v[174:177], v[0:15]
	s_waitcnt lgkmcnt(0)
	v_mfma_f32_32x32x16_bf16 v[0:15], v[232:235], v[178:181], v[0:15]
